# lora w/a epilogue loops: constant vector loaded once before the loop, no per-row-group vmcnt(0) (which also drained the previous store)
# speedup vs baseline: 1.0226x; 1.0030x over previous
.LBB0_301:
	s_or_b64 exec, exec, s[6:7]
	s_waitcnt vmcnt(3)
	v_and_b32_e32 v117, 0xffff0000, v58
	v_lshlrev_b32_e32 v118, 16, v58
	v_and_b32_e32 v58, 0xffff0000, v56
	v_lshlrev_b32_e32 v56, 16, v56
	v_sub_f32_e32 v60, v60, v56
	v_and_b32_e32 v72, 0xffff0000, v59
	v_lshlrev_b32_e32 v91, 16, v59
	v_and_b32_e32 v59, 0xffff0000, v57
	v_lshlrev_b32_e32 v57, 16, v57
	s_waitcnt vmcnt(1)
	v_fmac_f32_e32 v56, v68, v60
	v_sub_f32_e32 v60, v61, v58
	v_fmac_f32_e32 v58, v60, v69
	v_sub_f32_e32 v60, v62, v57
	v_fmac_f32_e32 v57, v60, v70
	v_add_f32_e32 v56, v56, v56
	v_add_f32_e32 v57, v57, v57
	v_mul_f32_e32 v56, 0x3fb8aa3b, v56
	v_mul_f32_e32 v57, 0x3fb8aa3b, v57
	v_sub_f32_e32 v33, v33, v117
	v_exp_f32_e32 v56, v56
	v_exp_f32_e32 v57, v57
	v_fmac_f32_e32 v117, v33, v65
	v_add_f32_e32 v33, v117, v117
	v_sub_f32_e32 v60, v63, v59
	v_mul_f32_e32 v33, 0x3fb8aa3b, v33
	v_fmac_f32_e32 v59, v60, v71
	v_exp_f32_e32 v60, v33
	v_sub_f32_e32 v33, v34, v91
	v_sub_f32_e32 v34, v35, v72
	v_fmac_f32_e32 v72, v34, v67
	v_pk_add_f32 v[34:35], v[56:57], 1.0 op_sel_hi:[1,0]
	v_sub_f32_e32 v32, v32, v118
	v_div_scale_f32 v56, s[4:5], v35, v35, 2.0
	v_rcp_f32_e32 v57, v56
	v_fmac_f32_e32 v118, v32, v64
	v_add_f32_e32 v58, v58, v58
	v_add_f32_e32 v59, v59, v59
	v_fma_f32 v62, -v56, v57, 1.0
	v_fmac_f32_e32 v57, v62, v57
	v_div_scale_f32 v62, vcc, 2.0, v35, 2.0
	v_mul_f32_e32 v63, v62, v57
	v_fma_f32 v64, -v56, v63, v62
	v_fmac_f32_e32 v63, v64, v57
	v_fma_f32 v56, -v56, v63, v62
	v_div_scale_f32 v62, s[4:5], v34, v34, 2.0
	v_rcp_f32_e32 v64, v62
	v_div_fmas_f32 v56, v56, v57, v63
	v_mul_f32_e32 v58, 0x3fb8aa3b, v58
	v_mul_f32_e32 v59, 0x3fb8aa3b, v59
	v_div_fixup_f32 v35, v56, v35, 2.0
	v_fma_f32 v56, -v62, v64, 1.0
	v_exp_f32_e32 v58, v58
	v_exp_f32_e32 v59, v59
	v_fmac_f32_e32 v64, v56, v64
	v_div_scale_f32 v56, vcc, 2.0, v34, 2.0
	v_mul_f32_e32 v63, v56, v64
	v_fma_f32 v57, -v62, v63, v56
	v_fmac_f32_e32 v63, v57, v64
	v_fma_f32 v62, -v62, v63, v56
	v_pk_add_f32 v[56:57], v[58:59], 1.0 op_sel_hi:[1,0]
	v_div_fmas_f32 v62, v62, v64, v63
	v_div_scale_f32 v58, s[4:5], v57, v57, 2.0
	v_rcp_f32_e32 v59, v58
	v_div_fixup_f32 v34, v62, v34, 2.0
	v_fmac_f32_e32 v91, v33, v66
	v_add_f32_e32 v32, v118, v118
	v_fma_f32 v62, -v58, v59, 1.0
	v_fmac_f32_e32 v59, v62, v59
	v_div_scale_f32 v62, vcc, 2.0, v57, 2.0
	v_mul_f32_e32 v63, v62, v59
	v_fma_f32 v64, -v58, v63, v62
	v_fmac_f32_e32 v63, v64, v59
	v_fma_f32 v58, -v58, v63, v62
	v_div_scale_f32 v62, s[4:5], v56, v56, 2.0
	v_rcp_f32_e32 v64, v62
	v_div_fmas_f32 v58, v58, v59, v63
	v_div_fixup_f32 v57, v58, v57, 2.0
	v_add_f32_e32 v33, v91, v91
	v_fma_f32 v58, -v62, v64, 1.0
	v_fmac_f32_e32 v64, v58, v64
	v_div_scale_f32 v58, vcc, 2.0, v56, 2.0
	v_mul_f32_e32 v59, v58, v64
	v_fma_f32 v63, -v62, v59, v58
	v_fmac_f32_e32 v59, v63, v64
	v_fma_f32 v58, -v62, v59, v58
	v_mul_f32_e32 v32, 0x3fb8aa3b, v32
	v_mul_f32_e32 v33, 0x3fb8aa3b, v33
	v_div_fmas_f32 v58, v58, v64, v59
	v_exp_f32_e32 v32, v32
	v_exp_f32_e32 v33, v33
	v_pk_add_f32 v[34:35], v[34:35], 1.0 op_sel_hi:[1,0] neg_lo:[1,0] neg_hi:[1,0]
	v_div_fixup_f32 v56, v58, v56, 2.0
	v_pk_add_f32 v[56:57], v[56:57], 1.0 op_sel_hi:[1,0] neg_lo:[1,0] neg_hi:[1,0]
	v_and_b32_sdwa v59, v34, v115 dst_sel:DWORD dst_unused:UNUSED_PAD src0_sel:WORD_1 src1_sel:DWORD
	v_and_b32_sdwa v58, v35, v115 dst_sel:DWORD dst_unused:UNUSED_PAD src0_sel:WORD_1 src1_sel:DWORD
	v_add3_u32 v59, v34, v59, s82
	v_and_b32_sdwa v34, v57, v115 dst_sel:DWORD dst_unused:UNUSED_PAD src0_sel:WORD_1 src1_sel:DWORD
	v_add3_u32 v58, v35, v58, s82
	v_and_b32_sdwa v35, v56, v115 dst_sel:DWORD dst_unused:UNUSED_PAD src0_sel:WORD_1 src1_sel:DWORD
	v_add3_u32 v34, v57, v34, s82
	v_add3_u32 v56, v56, v35, s82
	v_and_b32_e32 v57, 0xffff0000, v34
	v_pk_add_f32 v[34:35], v[32:33], 1.0 op_sel_hi:[1,0]
	v_and_b32_e32 v32, 0xffff0000, v56
	v_div_scale_f32 v62, s[4:5], v35, v35, 2.0
	v_rcp_f32_e32 v63, v62
	v_or_b32_sdwa v33, v57, v58 dst_sel:DWORD dst_unused:UNUSED_PAD src0_sel:DWORD src1_sel:WORD_1
	v_or_b32_sdwa v32, v32, v59 dst_sel:DWORD dst_unused:UNUSED_PAD src0_sel:DWORD src1_sel:WORD_1
	v_add_f32_e32 v61, v72, v72
	v_fma_f32 v56, -v62, v63, 1.0
	v_fmac_f32_e32 v63, v56, v63
	v_div_scale_f32 v56, vcc, 2.0, v35, 2.0
	v_mul_f32_e32 v57, v56, v63
	v_fma_f32 v58, -v62, v57, v56
	v_fmac_f32_e32 v57, v58, v63
	v_div_scale_f32 v58, s[4:5], v34, v34, 2.0
	v_rcp_f32_e32 v59, v58
	v_fma_f32 v56, -v62, v57, v56
	v_div_fmas_f32 v56, v56, v63, v57
	v_mul_f32_e32 v61, 0x3fb8aa3b, v61
	v_div_fixup_f32 v35, v56, v35, 2.0
	v_fma_f32 v56, -v58, v59, 1.0
	v_exp_f32_e32 v61, v61
	v_fmac_f32_e32 v59, v56, v59
	v_div_scale_f32 v56, vcc, 2.0, v34, 2.0
	v_mul_f32_e32 v62, v56, v59
	v_fma_f32 v57, -v58, v62, v56
	v_fmac_f32_e32 v62, v57, v59
	v_fma_f32 v58, -v58, v62, v56
	v_pk_add_f32 v[56:57], v[60:61], 1.0 op_sel_hi:[1,0]
	v_div_fmas_f32 v58, v58, v59, v62
	v_div_scale_f32 v60, s[4:5], v57, v57, 2.0
	v_rcp_f32_e32 v61, v60
	v_div_fixup_f32 v34, v58, v34, 2.0
	v_pk_add_f32 v[34:35], v[34:35], 1.0 op_sel_hi:[1,0] neg_lo:[1,0] neg_hi:[1,0]
	v_readlane_b32 s36, v236, 48
	v_fma_f32 v58, -v60, v61, 1.0
	v_fmac_f32_e32 v61, v58, v61
	v_div_scale_f32 v58, vcc, 2.0, v57, 2.0
	v_mul_f32_e32 v59, v58, v61
	v_fma_f32 v62, -v60, v59, v58
	v_fmac_f32_e32 v59, v62, v61
	v_fma_f32 v58, -v60, v59, v58
	v_div_scale_f32 v60, s[4:5], v56, v56, 2.0
	v_rcp_f32_e32 v62, v60
	v_div_fmas_f32 v58, v58, v61, v59
	v_div_fixup_f32 v57, v58, v57, 2.0
	v_readlane_b32 s38, v236, 50
	v_fma_f32 v58, -v60, v62, 1.0
	v_fmac_f32_e32 v62, v58, v62
	v_div_scale_f32 v58, vcc, 2.0, v56, 2.0
	v_mul_f32_e32 v59, v58, v62
	v_fma_f32 v61, -v60, v59, v58
	v_fmac_f32_e32 v59, v61, v62
	v_fma_f32 v58, -v60, v59, v58
	v_div_fmas_f32 v58, v58, v62, v59
	v_div_fixup_f32 v56, v58, v56, 2.0
	v_pk_add_f32 v[56:57], v[56:57], 1.0 op_sel_hi:[1,0] neg_lo:[1,0] neg_hi:[1,0]
	v_and_b32_sdwa v58, v35, v115 dst_sel:DWORD dst_unused:UNUSED_PAD src0_sel:WORD_1 src1_sel:DWORD
	v_and_b32_sdwa v59, v34, v115 dst_sel:DWORD dst_unused:UNUSED_PAD src0_sel:WORD_1 src1_sel:DWORD
	v_add3_u32 v34, v34, v59, s82
	v_add3_u32 v35, v35, v58, s82
	v_and_b32_sdwa v58, v57, v115 dst_sel:DWORD dst_unused:UNUSED_PAD src0_sel:WORD_1 src1_sel:DWORD
	v_and_b32_sdwa v59, v56, v115 dst_sel:DWORD dst_unused:UNUSED_PAD src0_sel:WORD_1 src1_sel:DWORD
	v_add3_u32 v57, v57, v58, s82
	v_add3_u32 v56, v56, v59, s82
	v_and_b32_e32 v58, 0xffff0000, v42
	v_lshlrev_b32_e32 v59, 16, v42
	v_and_b32_e32 v42, 0xffff0000, v40
	v_lshlrev_b32_e32 v40, 16, v40
	v_and_b32_e32 v57, 0xffff0000, v57
	v_and_b32_e32 v56, 0xffff0000, v56
	v_sub_f32_e32 v44, v44, v40
	v_or_b32_sdwa v35, v57, v35 dst_sel:DWORD dst_unused:UNUSED_PAD src0_sel:DWORD src1_sel:WORD_1
	v_or_b32_sdwa v34, v56, v34 dst_sel:DWORD dst_unused:UNUSED_PAD src0_sel:DWORD src1_sel:WORD_1
	v_and_b32_e32 v56, 0xffff0000, v43
	v_lshlrev_b32_e32 v57, 16, v43
	v_and_b32_e32 v43, 0xffff0000, v41
	v_lshlrev_b32_e32 v41, 16, v41
	v_fmac_f32_e32 v40, v52, v44
	v_sub_f32_e32 v44, v45, v42
	v_fmac_f32_e32 v42, v44, v53
	v_sub_f32_e32 v44, v46, v41
	v_fmac_f32_e32 v41, v44, v54
	v_add_f32_e32 v40, v40, v40
	v_add_f32_e32 v41, v41, v41
	v_mul_f32_e32 v40, 0x3fb8aa3b, v40
	v_mul_f32_e32 v41, 0x3fb8aa3b, v41
	v_sub_f32_e32 v37, v37, v58
	v_exp_f32_e32 v40, v40
	v_exp_f32_e32 v41, v41
	v_fmac_f32_e32 v58, v37, v49
	v_add_f32_e32 v37, v58, v58
	v_sub_f32_e32 v44, v47, v43
	v_mul_f32_e32 v37, 0x3fb8aa3b, v37
	v_fmac_f32_e32 v43, v44, v55
	v_exp_f32_e32 v44, v37
	v_sub_f32_e32 v37, v38, v57
	v_sub_f32_e32 v38, v39, v56
	v_fmac_f32_e32 v56, v38, v51
	v_pk_add_f32 v[38:39], v[40:41], 1.0 op_sel_hi:[1,0]
	v_sub_f32_e32 v36, v36, v59
	v_div_scale_f32 v40, s[4:5], v39, v39, 2.0
	v_rcp_f32_e32 v41, v40
	v_fmac_f32_e32 v59, v36, v48
	v_add_f32_e32 v42, v42, v42
	v_add_f32_e32 v43, v43, v43
	v_fma_f32 v46, -v40, v41, 1.0
	v_fmac_f32_e32 v41, v46, v41
	v_div_scale_f32 v46, vcc, 2.0, v39, 2.0
	v_mul_f32_e32 v47, v46, v41
	v_fma_f32 v48, -v40, v47, v46
	v_fmac_f32_e32 v47, v48, v41
	v_fma_f32 v40, -v40, v47, v46
	v_div_scale_f32 v46, s[4:5], v38, v38, 2.0
	v_rcp_f32_e32 v48, v46
	v_div_fmas_f32 v40, v40, v41, v47
	v_mul_f32_e32 v42, 0x3fb8aa3b, v42
	v_mul_f32_e32 v43, 0x3fb8aa3b, v43
	v_div_fixup_f32 v39, v40, v39, 2.0
	v_fma_f32 v40, -v46, v48, 1.0
	v_exp_f32_e32 v42, v42
	v_exp_f32_e32 v43, v43
	v_fmac_f32_e32 v48, v40, v48
	v_div_scale_f32 v40, vcc, 2.0, v38, 2.0
	v_mul_f32_e32 v47, v40, v48
	v_fma_f32 v41, -v46, v47, v40
	v_fmac_f32_e32 v47, v41, v48
	v_fma_f32 v46, -v46, v47, v40
	v_pk_add_f32 v[40:41], v[42:43], 1.0 op_sel_hi:[1,0]
	v_div_fmas_f32 v46, v46, v48, v47
	v_div_scale_f32 v42, s[4:5], v41, v41, 2.0
	v_rcp_f32_e32 v43, v42
	v_div_fixup_f32 v38, v46, v38, 2.0
	v_fmac_f32_e32 v57, v37, v50
	v_add_f32_e32 v36, v59, v59
	v_fma_f32 v46, -v42, v43, 1.0
	v_fmac_f32_e32 v43, v46, v43
	v_div_scale_f32 v46, vcc, 2.0, v41, 2.0
	v_mul_f32_e32 v47, v46, v43
	v_fma_f32 v48, -v42, v47, v46
	v_fmac_f32_e32 v47, v48, v43
	v_fma_f32 v42, -v42, v47, v46
	v_div_scale_f32 v46, s[4:5], v40, v40, 2.0
	v_rcp_f32_e32 v48, v46
	v_div_fmas_f32 v42, v42, v43, v47
	v_div_fixup_f32 v41, v42, v41, 2.0
	v_add_f32_e32 v37, v57, v57
	v_fma_f32 v42, -v46, v48, 1.0
	v_fmac_f32_e32 v48, v42, v48
	v_div_scale_f32 v42, vcc, 2.0, v40, 2.0
	v_mul_f32_e32 v43, v42, v48
	v_fma_f32 v47, -v46, v43, v42
	v_fmac_f32_e32 v43, v47, v48
	v_fma_f32 v42, -v46, v43, v42
	v_mul_f32_e32 v36, 0x3fb8aa3b, v36
	v_mul_f32_e32 v37, 0x3fb8aa3b, v37
	v_div_fmas_f32 v42, v42, v48, v43
	v_exp_f32_e32 v36, v36
	v_exp_f32_e32 v37, v37
	v_pk_add_f32 v[38:39], v[38:39], 1.0 op_sel_hi:[1,0] neg_lo:[1,0] neg_hi:[1,0]
	v_div_fixup_f32 v40, v42, v40, 2.0
	v_pk_add_f32 v[40:41], v[40:41], 1.0 op_sel_hi:[1,0] neg_lo:[1,0] neg_hi:[1,0]
	v_and_b32_sdwa v43, v38, v115 dst_sel:DWORD dst_unused:UNUSED_PAD src0_sel:WORD_1 src1_sel:DWORD
	v_and_b32_sdwa v42, v39, v115 dst_sel:DWORD dst_unused:UNUSED_PAD src0_sel:WORD_1 src1_sel:DWORD
	v_add3_u32 v43, v38, v43, s82
	v_and_b32_sdwa v38, v41, v115 dst_sel:DWORD dst_unused:UNUSED_PAD src0_sel:WORD_1 src1_sel:DWORD
	v_add3_u32 v42, v39, v42, s82
	v_and_b32_sdwa v39, v40, v115 dst_sel:DWORD dst_unused:UNUSED_PAD src0_sel:WORD_1 src1_sel:DWORD
	v_add3_u32 v38, v41, v38, s82
	v_add3_u32 v40, v40, v39, s82
	v_and_b32_e32 v41, 0xffff0000, v38
	v_pk_add_f32 v[38:39], v[36:37], 1.0 op_sel_hi:[1,0]
	v_and_b32_e32 v36, 0xffff0000, v40
	v_div_scale_f32 v46, s[4:5], v39, v39, 2.0
	v_rcp_f32_e32 v47, v46
	v_or_b32_sdwa v37, v41, v42 dst_sel:DWORD dst_unused:UNUSED_PAD src0_sel:DWORD src1_sel:WORD_1
	v_or_b32_sdwa v36, v36, v43 dst_sel:DWORD dst_unused:UNUSED_PAD src0_sel:DWORD src1_sel:WORD_1
	v_add_f32_e32 v45, v56, v56
	v_fma_f32 v40, -v46, v47, 1.0
	v_fmac_f32_e32 v47, v40, v47
	v_div_scale_f32 v40, vcc, 2.0, v39, 2.0
	v_mul_f32_e32 v41, v40, v47
	v_fma_f32 v42, -v46, v41, v40
	v_fmac_f32_e32 v41, v42, v47
	v_div_scale_f32 v42, s[4:5], v38, v38, 2.0
	v_rcp_f32_e32 v43, v42
	v_fma_f32 v40, -v46, v41, v40
	v_div_fmas_f32 v40, v40, v47, v41
	v_mul_f32_e32 v45, 0x3fb8aa3b, v45
	v_div_fixup_f32 v39, v40, v39, 2.0
	v_fma_f32 v40, -v42, v43, 1.0
	v_exp_f32_e32 v45, v45
	v_fmac_f32_e32 v43, v40, v43
	v_div_scale_f32 v40, vcc, 2.0, v38, 2.0
	v_mul_f32_e32 v46, v40, v43
	v_fma_f32 v41, -v42, v46, v40
	v_fmac_f32_e32 v46, v41, v43
	v_fma_f32 v42, -v42, v46, v40
	v_pk_add_f32 v[40:41], v[44:45], 1.0 op_sel_hi:[1,0]
	v_div_fmas_f32 v42, v42, v43, v46
	v_div_scale_f32 v44, s[4:5], v41, v41, 2.0
	v_rcp_f32_e32 v45, v44
	v_div_fixup_f32 v38, v42, v38, 2.0
	v_pk_add_f32 v[38:39], v[38:39], 1.0 op_sel_hi:[1,0] neg_lo:[1,0] neg_hi:[1,0]
	v_readlane_b32 s39, v236, 51
	v_fma_f32 v42, -v44, v45, 1.0
	v_fmac_f32_e32 v45, v42, v45
	v_div_scale_f32 v42, vcc, 2.0, v41, 2.0
	v_mul_f32_e32 v43, v42, v45
	v_fma_f32 v46, -v44, v43, v42
	v_fmac_f32_e32 v43, v46, v45
	v_fma_f32 v42, -v44, v43, v42
	v_div_scale_f32 v44, s[4:5], v40, v40, 2.0
	v_rcp_f32_e32 v46, v44
	v_div_fmas_f32 v42, v42, v45, v43
	v_div_fixup_f32 v41, v42, v41, 2.0
	v_readlane_b32 s16, v238, 32
	v_fma_f32 v42, -v44, v46, 1.0
	v_fmac_f32_e32 v46, v42, v46
	v_div_scale_f32 v42, vcc, 2.0, v40, 2.0
	v_mul_f32_e32 v43, v42, v46
	v_fma_f32 v45, -v44, v43, v42
	v_fmac_f32_e32 v43, v45, v46
	v_fma_f32 v42, -v44, v43, v42
	v_div_fmas_f32 v42, v42, v46, v43
	v_div_fixup_f32 v40, v42, v40, 2.0
	v_pk_add_f32 v[40:41], v[40:41], 1.0 op_sel_hi:[1,0] neg_lo:[1,0] neg_hi:[1,0]
	v_and_b32_sdwa v42, v39, v115 dst_sel:DWORD dst_unused:UNUSED_PAD src0_sel:WORD_1 src1_sel:DWORD
	v_and_b32_sdwa v43, v38, v115 dst_sel:DWORD dst_unused:UNUSED_PAD src0_sel:WORD_1 src1_sel:DWORD
	v_add3_u32 v38, v38, v43, s82
	v_add3_u32 v39, v39, v42, s82
	v_and_b32_sdwa v42, v41, v115 dst_sel:DWORD dst_unused:UNUSED_PAD src0_sel:WORD_1 src1_sel:DWORD
	v_and_b32_sdwa v43, v40, v115 dst_sel:DWORD dst_unused:UNUSED_PAD src0_sel:WORD_1 src1_sel:DWORD
	v_add3_u32 v41, v41, v42, s82
	v_add3_u32 v40, v40, v43, s82
	v_and_b32_e32 v41, 0xffff0000, v41
	v_and_b32_e32 v40, 0xffff0000, v40
	v_or_b32_sdwa v39, v41, v39 dst_sel:DWORD dst_unused:UNUSED_PAD src0_sel:DWORD src1_sel:WORD_1
	v_or_b32_sdwa v38, v40, v38 dst_sel:DWORD dst_unused:UNUSED_PAD src0_sel:DWORD src1_sel:WORD_1
	v_and_b32_e32 v40, 0xffff0000, v15
	v_lshlrev_b32_e32 v41, 16, v15
	v_and_b32_e32 v15, 0xffff0000, v12
	v_lshlrev_b32_e32 v12, 16, v12
	v_and_b32_e32 v42, 0xffff0000, v14
	v_lshlrev_b32_e32 v43, 16, v14
	v_sub_f32_e32 v14, v20, v12
	v_fmac_f32_e32 v12, v28, v14
	v_add_f32_e32 v12, v12, v12
	v_mul_f32_e32 v12, 0x3fb8aa3b, v12
	v_exp_f32_e32 v14, v12
	v_sub_f32_e32 v12, v21, v15
	v_fmac_f32_e32 v15, v12, v29
	v_add_f32_e32 v12, v15, v15
	v_and_b32_e32 v44, 0xffff0000, v13
	v_lshlrev_b32_e32 v13, 16, v13
	v_mul_f32_e32 v12, 0x3fb8aa3b, v12
	v_exp_f32_e32 v20, v12
	v_sub_f32_e32 v12, v22, v13
	v_fmac_f32_e32 v13, v12, v30
	v_add_f32_e32 v12, v13, v13
	v_mul_f32_e32 v12, 0x3fb8aa3b, v12
	v_exp_f32_e32 v15, v12
	v_sub_f32_e32 v12, v23, v44
	v_sub_f32_e32 v9, v9, v42
	v_fmac_f32_e32 v44, v12, v31
	v_fmac_f32_e32 v42, v9, v25
	v_add_f32_e32 v12, v44, v44
	v_add_f32_e32 v9, v42, v42
	v_mul_f32_e32 v12, 0x3fb8aa3b, v12
	v_mul_f32_e32 v9, 0x3fb8aa3b, v9
	v_exp_f32_e32 v21, v12
	v_exp_f32_e32 v12, v9
	v_sub_f32_e32 v9, v10, v41
	v_sub_f32_e32 v10, v11, v40
	v_fmac_f32_e32 v40, v10, v27
	v_pk_add_f32 v[10:11], v[14:15], 1.0 op_sel_hi:[1,0]
	v_sub_f32_e32 v8, v8, v43
	v_div_scale_f32 v14, s[4:5], v11, v11, 2.0
	v_rcp_f32_e32 v15, v14
	v_fmac_f32_e32 v43, v8, v24
	v_fmac_f32_e32 v41, v9, v26
	v_add_f32_e32 v8, v43, v43
	v_fma_f32 v22, -v14, v15, 1.0
	v_fmac_f32_e32 v15, v22, v15
	v_div_scale_f32 v22, vcc, 2.0, v11, 2.0
	v_mul_f32_e32 v23, v22, v15
	v_fma_f32 v24, -v14, v23, v22
	v_fmac_f32_e32 v23, v24, v15
	v_fma_f32 v14, -v14, v23, v22
	v_div_scale_f32 v22, s[4:5], v10, v10, 2.0
	v_rcp_f32_e32 v24, v22
	v_div_fmas_f32 v14, v14, v15, v23
	v_div_fixup_f32 v11, v14, v11, 2.0
	v_add_f32_e32 v9, v41, v41
	v_fma_f32 v14, -v22, v24, 1.0
	v_fmac_f32_e32 v24, v14, v24
	v_div_scale_f32 v14, vcc, 2.0, v10, 2.0
	v_mul_f32_e32 v23, v14, v24
	v_fma_f32 v15, -v22, v23, v14
	v_fmac_f32_e32 v23, v15, v24
	v_fma_f32 v22, -v22, v23, v14
	v_pk_add_f32 v[14:15], v[20:21], 1.0 op_sel_hi:[1,0]
	v_div_fmas_f32 v22, v22, v24, v23
	v_div_scale_f32 v20, s[4:5], v15, v15, 2.0
	v_rcp_f32_e32 v21, v20
	v_div_fixup_f32 v10, v22, v10, 2.0
	v_mul_f32_e32 v8, 0x3fb8aa3b, v8
	v_mul_f32_e32 v9, 0x3fb8aa3b, v9
	v_fma_f32 v22, -v20, v21, 1.0
	v_fmac_f32_e32 v21, v22, v21
	v_div_scale_f32 v22, vcc, 2.0, v15, 2.0
	v_mul_f32_e32 v23, v22, v21
	v_fma_f32 v24, -v20, v23, v22
	v_fmac_f32_e32 v23, v24, v21
	v_fma_f32 v20, -v20, v23, v22
	v_div_scale_f32 v22, s[4:5], v14, v14, 2.0
	v_rcp_f32_e32 v24, v22
	v_div_fmas_f32 v20, v20, v21, v23
	v_div_fixup_f32 v15, v20, v15, 2.0
	v_exp_f32_e32 v8, v8
	v_fma_f32 v20, -v22, v24, 1.0
	v_fmac_f32_e32 v24, v20, v24
	v_div_scale_f32 v20, vcc, 2.0, v14, 2.0
	v_mul_f32_e32 v21, v20, v24
	v_fma_f32 v23, -v22, v21, v20
	v_fmac_f32_e32 v21, v23, v24
	v_fma_f32 v20, -v22, v21, v20
	v_div_fmas_f32 v20, v20, v24, v21
	v_exp_f32_e32 v9, v9
	v_pk_add_f32 v[10:11], v[10:11], 1.0 op_sel_hi:[1,0] neg_lo:[1,0] neg_hi:[1,0]
	v_div_fixup_f32 v14, v20, v14, 2.0
	v_pk_add_f32 v[14:15], v[14:15], 1.0 op_sel_hi:[1,0] neg_lo:[1,0] neg_hi:[1,0]
	v_and_b32_sdwa v21, v10, v115 dst_sel:DWORD dst_unused:UNUSED_PAD src0_sel:WORD_1 src1_sel:DWORD
	v_and_b32_sdwa v20, v11, v115 dst_sel:DWORD dst_unused:UNUSED_PAD src0_sel:WORD_1 src1_sel:DWORD
	v_add3_u32 v21, v10, v21, s82
	v_and_b32_sdwa v10, v15, v115 dst_sel:DWORD dst_unused:UNUSED_PAD src0_sel:WORD_1 src1_sel:DWORD
	v_add3_u32 v20, v11, v20, s82
	v_and_b32_sdwa v11, v14, v115 dst_sel:DWORD dst_unused:UNUSED_PAD src0_sel:WORD_1 src1_sel:DWORD
	v_add3_u32 v10, v15, v10, s82
	v_add3_u32 v14, v14, v11, s82
	v_and_b32_e32 v15, 0xffff0000, v10
	v_pk_add_f32 v[10:11], v[8:9], 1.0 op_sel_hi:[1,0]
	v_and_b32_e32 v8, 0xffff0000, v14
	v_div_scale_f32 v24, s[4:5], v11, v11, 2.0
	v_rcp_f32_e32 v25, v24
	v_or_b32_sdwa v9, v15, v20 dst_sel:DWORD dst_unused:UNUSED_PAD src0_sel:DWORD src1_sel:WORD_1
	v_or_b32_sdwa v8, v8, v21 dst_sel:DWORD dst_unused:UNUSED_PAD src0_sel:DWORD src1_sel:WORD_1
	global_load_dwordx4 v[20:23], v[82:83], off
	v_fma_f32 v14, -v24, v25, 1.0
	v_fmac_f32_e32 v25, v14, v25
	v_div_scale_f32 v14, vcc, 2.0, v11, 2.0
	v_mul_f32_e32 v15, v14, v25
	v_fma_f32 v26, -v24, v15, v14
	v_fmac_f32_e32 v15, v26, v25
	v_fma_f32 v14, -v24, v15, v14
	v_div_fmas_f32 v14, v14, v25, v15
	global_load_dwordx4 v[24:27], v[82:83], off offset:16
	v_div_scale_f32 v28, s[4:5], v10, v10, 2.0
	v_rcp_f32_e32 v29, v28
	v_add_f32_e32 v13, v40, v40
	v_mul_f32_e32 v13, 0x3fb8aa3b, v13
	v_exp_f32_e32 v13, v13
	v_div_fixup_f32 v11, v14, v11, 2.0
	v_fma_f32 v14, -v28, v29, 1.0
	v_fmac_f32_e32 v29, v14, v29
	v_div_scale_f32 v14, vcc, 2.0, v10, 2.0
	v_mul_f32_e32 v15, v14, v29
	v_fma_f32 v30, -v28, v15, v14
	v_fmac_f32_e32 v15, v30, v29
	v_pk_add_f32 v[12:13], v[12:13], 1.0 op_sel_hi:[1,0]
	v_fma_f32 v14, -v28, v15, v14
	v_div_scale_f32 v28, s[4:5], v13, v13, 2.0
	v_rcp_f32_e32 v30, v28
	v_div_fmas_f32 v14, v14, v29, v15
	v_div_fixup_f32 v10, v14, v10, 2.0
	v_pk_add_f32 v[10:11], v[10:11], 1.0 op_sel_hi:[1,0] neg_lo:[1,0] neg_hi:[1,0]
	v_fma_f32 v14, -v28, v30, 1.0
	v_fmac_f32_e32 v30, v14, v30
	v_div_scale_f32 v14, vcc, 2.0, v13, 2.0
	v_mul_f32_e32 v15, v14, v30
	v_fma_f32 v29, -v28, v15, v14
	v_fmac_f32_e32 v15, v29, v30
	v_fma_f32 v14, -v28, v15, v14
	v_div_scale_f32 v28, s[4:5], v12, v12, 2.0
	v_rcp_f32_e32 v29, v28
	v_div_fmas_f32 v14, v14, v30, v15
	v_div_fixup_f32 v13, v14, v13, 2.0
	s_lshl_b32 s4, s0, 7
	v_fma_f32 v14, -v28, v29, 1.0
	v_fmac_f32_e32 v29, v14, v29
	v_div_scale_f32 v14, vcc, 2.0, v12, 2.0
	v_mul_f32_e32 v15, v14, v29
	v_fma_f32 v30, -v28, v15, v14
	v_fmac_f32_e32 v15, v30, v29
	v_fma_f32 v14, -v28, v15, v14
	v_div_fmas_f32 v14, v14, v29, v15
	v_div_fixup_f32 v12, v14, v12, 2.0
	v_pk_add_f32 v[12:13], v[12:13], 1.0 op_sel_hi:[1,0] neg_lo:[1,0] neg_hi:[1,0]
	v_and_b32_sdwa v14, v11, v115 dst_sel:DWORD dst_unused:UNUSED_PAD src0_sel:WORD_1 src1_sel:DWORD
	v_and_b32_sdwa v15, v10, v115 dst_sel:DWORD dst_unused:UNUSED_PAD src0_sel:WORD_1 src1_sel:DWORD
	v_add3_u32 v10, v10, v15, s82
	v_add3_u32 v11, v11, v14, s82
	v_and_b32_sdwa v14, v13, v115 dst_sel:DWORD dst_unused:UNUSED_PAD src0_sel:WORD_1 src1_sel:DWORD
	v_and_b32_sdwa v15, v12, v115 dst_sel:DWORD dst_unused:UNUSED_PAD src0_sel:WORD_1 src1_sel:DWORD
	v_add3_u32 v13, v13, v14, s82
	v_add3_u32 v12, v12, v15, s82
	v_and_b32_e32 v13, 0xffff0000, v13
	v_and_b32_e32 v12, 0xffff0000, v12
	v_or_b32_sdwa v11, v13, v11 dst_sel:DWORD dst_unused:UNUSED_PAD src0_sel:DWORD src1_sel:WORD_1
	v_or_b32_sdwa v10, v12, v10 dst_sel:DWORD dst_unused:UNUSED_PAD src0_sel:DWORD src1_sel:WORD_1
	s_waitcnt vmcnt(2)
	v_and_b32_e32 v12, 0xffff0000, v19
	v_lshlrev_b32_e32 v13, 16, v19
	v_and_b32_e32 v19, 0xffff0000, v16
	v_lshlrev_b32_e32 v16, 16, v16
	v_sub_f32_e32 v4, v4, v16
	v_lshlrev_b32_e32 v15, 16, v18
	v_sub_f32_e32 v0, v0, v15
	v_and_b32_e32 v14, 0xffff0000, v18
	v_and_b32_e32 v18, 0xffff0000, v17
	v_lshlrev_b32_e32 v17, 16, v17
	s_waitcnt vmcnt(1)
	v_fmac_f32_e32 v16, v20, v4
	v_add_f32_e32 v4, v16, v16
	v_mul_f32_e32 v4, 0x3fb8aa3b, v4
	v_exp_f32_e32 v20, v4
	v_sub_f32_e32 v4, v5, v19
	v_fmac_f32_e32 v19, v4, v21
	v_add_f32_e32 v4, v19, v19
	v_mul_f32_e32 v4, 0x3fb8aa3b, v4
	v_exp_f32_e32 v28, v4
	v_sub_f32_e32 v4, v6, v17
	s_waitcnt vmcnt(0)
	v_fmac_f32_e32 v15, v0, v24
	v_add_f32_e32 v0, v15, v15
	v_mul_f32_e32 v0, 0x3fb8aa3b, v0
	v_fmac_f32_e32 v17, v4, v22
	v_exp_f32_e32 v22, v0
	v_sub_f32_e32 v0, v1, v14
	v_add_f32_e32 v4, v17, v17
	v_fmac_f32_e32 v14, v0, v25
	v_mul_f32_e32 v4, 0x3fb8aa3b, v4
	v_add_f32_e32 v0, v14, v14
	v_exp_f32_e32 v21, v4
	v_mul_f32_e32 v0, 0x3fb8aa3b, v0
	v_exp_f32_e32 v24, v0
	v_sub_f32_e32 v0, v2, v13
	v_fmac_f32_e32 v13, v0, v26
	v_add_f32_e32 v0, v13, v13
	v_sub_f32_e32 v4, v7, v18
	v_mul_f32_e32 v0, 0x3fb8aa3b, v0
	v_pk_add_f32 v[20:21], v[20:21], 1.0 op_sel_hi:[1,0]
	v_fmac_f32_e32 v18, v4, v23
	v_exp_f32_e32 v23, v0
	v_sub_f32_e32 v0, v3, v12
	v_div_scale_f32 v26, s[6:7], v21, v21, 2.0
	v_fmac_f32_e32 v12, v0, v27
	v_rcp_f32_e32 v27, v26
	s_and_b32 s4, s4, 0x180
	v_add_f32_e32 v4, v18, v18
	v_add_f32_e32 v0, v12, v12
	v_add_lshl_u32 v72, s4, v105, 7
	v_mul_f32_e32 v4, 0x3fb8aa3b, v4
	v_mul_f32_e32 v0, 0x3fb8aa3b, v0
	v_lshl_add_u64 v[16:17], v[84:85], 0, v[72:73]
	v_exp_f32_e32 v29, v4
	v_exp_f32_e32 v25, v0
	global_load_dwordx4 v[0:3], v[16:17], off offset:48
	global_load_dwordx4 v[4:7], v[16:17], off offset:32
	global_load_dwordx4 v[12:15], v[16:17], off offset:16
	s_nop 0
	global_load_dwordx4 v[16:19], v[16:17], off
	s_barrier
	ds_write_b128 v112, v[8:11]
	ds_write_b128 v112, v[36:39] offset:16
	ds_write_b128 v112, v[32:35] offset:32
	v_fma_f32 v8, -v26, v27, 1.0
	v_fmac_f32_e32 v27, v8, v27
	v_div_scale_f32 v8, vcc, 2.0, v21, 2.0
	v_mul_f32_e32 v9, v8, v27
	v_fma_f32 v10, -v26, v9, v8
	v_fmac_f32_e32 v9, v10, v27
	v_div_scale_f32 v10, s[6:7], v20, v20, 2.0
	v_fma_f32 v8, -v26, v9, v8
	v_rcp_f32_e32 v26, v10
	v_div_fmas_f32 v8, v8, v27, v9
	v_div_fixup_f32 v9, v8, v21, 2.0
	s_and_b32 s5, s1, 0xffffff80
	v_fma_f32 v8, -v10, v26, 1.0
	v_fmac_f32_e32 v26, v8, v26
	v_div_scale_f32 v8, vcc, 2.0, v20, 2.0
	v_mul_f32_e32 v21, v8, v26
	v_fma_f32 v11, -v10, v21, v8
	v_fmac_f32_e32 v21, v11, v26
	v_fma_f32 v8, -v10, v21, v8
	v_pk_add_f32 v[10:11], v[28:29], 1.0 op_sel_hi:[1,0]
	v_div_fmas_f32 v8, v8, v26, v21
	v_div_scale_f32 v27, s[6:7], v11, v11, 2.0
	v_rcp_f32_e32 v28, v27
	v_div_fixup_f32 v8, v8, v20, 2.0
	v_pk_add_f32 v[8:9], v[8:9], 1.0 op_sel_hi:[1,0] neg_lo:[1,0] neg_hi:[1,0]
	v_readlane_b32 s20, v238, 36
	v_fma_f32 v20, -v27, v28, 1.0
	v_fmac_f32_e32 v28, v20, v28
	v_div_scale_f32 v20, vcc, 2.0, v11, 2.0
	v_mul_f32_e32 v21, v20, v28
	v_fma_f32 v26, -v27, v21, v20
	v_fmac_f32_e32 v21, v26, v28
	v_div_scale_f32 v26, s[6:7], v10, v10, 2.0
	v_fma_f32 v20, -v27, v21, v20
	v_rcp_f32_e32 v27, v26
	v_div_fmas_f32 v20, v20, v28, v21
	v_div_fixup_f32 v11, v20, v11, 2.0
	v_readlane_b32 s21, v238, 37
	v_fma_f32 v20, -v26, v27, 1.0
	v_fmac_f32_e32 v27, v20, v27
	v_div_scale_f32 v20, vcc, 2.0, v10, 2.0
	v_mul_f32_e32 v21, v20, v27
	v_fma_f32 v28, -v26, v21, v20
	v_fmac_f32_e32 v21, v28, v27
	v_fma_f32 v20, -v26, v21, v20
	v_div_fmas_f32 v20, v20, v27, v21
	v_div_fixup_f32 v10, v20, v10, 2.0
	v_pk_add_f32 v[10:11], v[10:11], 1.0 op_sel_hi:[1,0] neg_lo:[1,0] neg_hi:[1,0]
	v_and_b32_sdwa v20, v9, v115 dst_sel:DWORD dst_unused:UNUSED_PAD src0_sel:WORD_1 src1_sel:DWORD
	v_and_b32_sdwa v21, v8, v115 dst_sel:DWORD dst_unused:UNUSED_PAD src0_sel:WORD_1 src1_sel:DWORD
	v_add3_u32 v9, v9, v20, s82
	v_and_b32_sdwa v20, v11, v115 dst_sel:DWORD dst_unused:UNUSED_PAD src0_sel:WORD_1 src1_sel:DWORD
	v_add3_u32 v8, v8, v21, s82
	v_and_b32_sdwa v21, v10, v115 dst_sel:DWORD dst_unused:UNUSED_PAD src0_sel:WORD_1 src1_sel:DWORD
	v_add3_u32 v11, v11, v20, s82
	v_add3_u32 v20, v10, v21, s82
	v_and_b32_e32 v21, 0xffff0000, v11
	v_pk_add_f32 v[10:11], v[22:23], 1.0 op_sel_hi:[1,0]
	v_and_b32_e32 v20, 0xffff0000, v20
	v_div_scale_f32 v22, s[6:7], v11, v11, 2.0
	v_rcp_f32_e32 v23, v22
	v_or_b32_sdwa v8, v20, v8 dst_sel:DWORD dst_unused:UNUSED_PAD src0_sel:DWORD src1_sel:WORD_1
	v_or_b32_sdwa v9, v21, v9 dst_sel:DWORD dst_unused:UNUSED_PAD src0_sel:DWORD src1_sel:WORD_1
	v_readlane_b32 s37, v236, 49
	v_fma_f32 v20, -v22, v23, 1.0
	v_fmac_f32_e32 v23, v20, v23
	v_div_scale_f32 v20, vcc, 2.0, v11, 2.0
	v_mul_f32_e32 v21, v20, v23
	v_fma_f32 v26, -v22, v21, v20
	v_fmac_f32_e32 v21, v26, v23
	v_fma_f32 v20, -v22, v21, v20
	v_div_scale_f32 v22, s[6:7], v10, v10, 2.0
	v_rcp_f32_e32 v26, v22
	v_div_fmas_f32 v20, v20, v23, v21
	v_div_fixup_f32 v11, v20, v11, 2.0
	v_readlane_b32 s40, v236, 52
	v_fma_f32 v20, -v22, v26, 1.0
	v_fmac_f32_e32 v26, v20, v26
	v_div_scale_f32 v20, vcc, 2.0, v10, 2.0
	v_mul_f32_e32 v23, v20, v26
	v_fma_f32 v21, -v22, v23, v20
	v_fmac_f32_e32 v23, v21, v26
	v_fma_f32 v22, -v22, v23, v20
	v_pk_add_f32 v[20:21], v[24:25], 1.0 op_sel_hi:[1,0]
	v_div_fmas_f32 v22, v22, v26, v23
	v_div_scale_f32 v24, s[6:7], v21, v21, 2.0
	v_rcp_f32_e32 v25, v24
	v_div_fixup_f32 v10, v22, v10, 2.0
	v_pk_add_f32 v[10:11], v[10:11], 1.0 op_sel_hi:[1,0] neg_lo:[1,0] neg_hi:[1,0]
	v_readlane_b32 s41, v236, 53
	v_fma_f32 v22, -v24, v25, 1.0
	v_fmac_f32_e32 v25, v22, v25
	v_div_scale_f32 v22, vcc, 2.0, v21, 2.0
	v_mul_f32_e32 v23, v22, v25
	v_fma_f32 v26, -v24, v23, v22
	v_fmac_f32_e32 v23, v26, v25
	v_fma_f32 v22, -v24, v23, v22
	v_div_scale_f32 v24, s[6:7], v20, v20, 2.0
	v_rcp_f32_e32 v26, v24
	v_div_fmas_f32 v22, v22, v25, v23
	v_div_fixup_f32 v21, v22, v21, 2.0
	s_mov_b32 s6, 0
	v_fma_f32 v22, -v24, v26, 1.0
	v_fmac_f32_e32 v26, v22, v26
	v_div_scale_f32 v22, vcc, 2.0, v20, 2.0
	v_mul_f32_e32 v23, v22, v26
	v_fma_f32 v25, -v24, v23, v22
	v_fmac_f32_e32 v23, v25, v26
	v_fma_f32 v22, -v24, v23, v22
	v_div_fmas_f32 v22, v22, v26, v23
	v_div_fixup_f32 v20, v22, v20, 2.0
	v_pk_add_f32 v[20:21], v[20:21], 1.0 op_sel_hi:[1,0] neg_lo:[1,0] neg_hi:[1,0]
	v_and_b32_sdwa v22, v11, v115 dst_sel:DWORD dst_unused:UNUSED_PAD src0_sel:WORD_1 src1_sel:DWORD
	v_and_b32_sdwa v23, v10, v115 dst_sel:DWORD dst_unused:UNUSED_PAD src0_sel:WORD_1 src1_sel:DWORD
	v_add3_u32 v10, v10, v23, s82
	v_add3_u32 v11, v11, v22, s82
	v_and_b32_sdwa v22, v21, v115 dst_sel:DWORD dst_unused:UNUSED_PAD src0_sel:WORD_1 src1_sel:DWORD
	v_and_b32_sdwa v23, v20, v115 dst_sel:DWORD dst_unused:UNUSED_PAD src0_sel:WORD_1 src1_sel:DWORD
	v_add3_u32 v21, v21, v22, s82
	v_add3_u32 v20, v20, v23, s82
	v_and_b32_e32 v21, 0xffff0000, v21
	v_and_b32_e32 v20, 0xffff0000, v20
	v_or_b32_sdwa v11, v21, v11 dst_sel:DWORD dst_unused:UNUSED_PAD src0_sel:DWORD src1_sel:WORD_1
	v_or_b32_sdwa v10, v20, v10 dst_sel:DWORD dst_unused:UNUSED_PAD src0_sel:DWORD src1_sel:WORD_1
	ds_write_b128 v112, v[8:11] offset:48
	s_waitcnt vmcnt(0)
	ds_write_b128 v112, v[16:19] offset:18432
	ds_write_b128 v112, v[12:15] offset:18448
	ds_write_b128 v112, v[4:7] offset:18464
	ds_write_b128 v112, v[0:3] offset:18480
	s_waitcnt lgkmcnt(0)
	s_barrier
	ds_read_b128 v[0:3], v113
	ds_read_b128 v[4:7], v114 offset:18432
	ds_read_b128 v[16:19], v114 offset:23040
	ds_read_b128 v[20:23], v113 offset:4608
	s_waitcnt lgkmcnt(2)
	v_mfma_f32_32x32x16_bf16 v[32:47], v[0:3], v[4:7], 0
	ds_read_b128 v[64:67], v113 offset:32
	ds_read_b128 v[68:71], v114 offset:18464
	ds_read_b128 v[118:121], v114 offset:23072
	v_readlane_b32 s42, v236, 54
	v_readlane_b32 s43, v236, 55
	v_readlane_b32 s44, v236, 56
	v_readlane_b32 s45, v236, 57
	v_readlane_b32 s46, v236, 58
	s_waitcnt lgkmcnt(4)
	v_mfma_f32_32x32x16_bf16 v[48:63], v[0:3], v[16:19], 0
	v_readlane_b32 s47, v236, 59
	v_readlane_b32 s48, v236, 60
	v_readlane_b32 s49, v236, 61
	v_readlane_b32 s50, v236, 62
	v_readlane_b32 s51, v236, 63
	v_readlane_b32 s17, v238, 33
	v_readlane_b32 s18, v238, 34
	s_waitcnt lgkmcnt(1)
	v_mfma_f32_32x32x16_bf16 v[32:47], v[64:67], v[68:71], v[32:47]
	v_readlane_b32 s19, v238, 35
	v_readlane_b32 s22, v238, 38
	v_readlane_b32 s23, v238, 39
	v_readlane_b32 s24, v238, 40
	v_readlane_b32 s25, v238, 41
	v_readlane_b32 s26, v238, 42
	v_readlane_b32 s27, v238, 43
	s_waitcnt lgkmcnt(0)
	v_mfma_f32_32x32x16_bf16 v[48:63], v[64:67], v[118:121], v[48:63]
	ds_read_b128 v[64:67], v113 offset:4640
	v_readlane_b32 s28, v238, 44
	v_readlane_b32 s29, v238, 45
	v_readlane_b32 s30, v238, 46
	v_readlane_b32 s31, v238, 47
	v_mfma_f32_32x32x16_bf16 v[0:15], v[20:23], v[4:7], 0
	v_mfma_f32_32x32x16_bf16 v[16:31], v[20:23], v[16:19], 0
	s_waitcnt lgkmcnt(0)
	v_mfma_f32_32x32x16_bf16 v[0:15], v[64:67], v[68:71], v[0:15]
	v_mfma_f32_32x32x16_bf16 v[16:31], v[64:67], v[118:121], v[16:31]
	ds_read_b128 v[64:67], v113 offset:64
	ds_read_b128 v[68:71], v114 offset:18496
	ds_read_b128 v[118:121], v114 offset:23104
	s_waitcnt lgkmcnt(1)
	v_mfma_f32_32x32x16_bf16 v[32:47], v[64:67], v[68:71], v[32:47]
	s_waitcnt lgkmcnt(0)
	v_mfma_f32_32x32x16_bf16 v[48:63], v[64:67], v[118:121], v[48:63]
	ds_read_b128 v[64:67], v113 offset:4672
	s_waitcnt lgkmcnt(0)
	v_mfma_f32_32x32x16_bf16 v[0:15], v[64:67], v[68:71], v[0:15]
	v_mfma_f32_32x32x16_bf16 v[16:31], v[64:67], v[118:121], v[16:31]
	ds_read_b128 v[64:67], v113 offset:96
	ds_read_b128 v[68:71], v114 offset:18528
	ds_read_b128 v[118:121], v114 offset:23136
	ds_read_b128 v[122:125], v113 offset:4704
	s_waitcnt lgkmcnt(0)
	s_barrier
	v_mfma_f32_32x32x16_bf16 v[32:47], v[64:67], v[68:71], v[32:47]
	v_mfma_f32_32x32x16_bf16 v[48:63], v[64:67], v[118:121], v[48:63]
	s_nop 11
	ds_write2_b32 v92, v32, v48 offset1:32
	ds_write2_b32 v92, v33, v49 offset0:132 offset1:164
	v_add_u32_e32 v32, 0x400, v92
	ds_write2_b32 v32, v34, v50 offset0:8 offset1:40
	ds_write2_b32 v32, v35, v51 offset0:140 offset1:172
	v_add_u32_e32 v32, 0x1000, v92
	v_mfma_f32_32x32x16_bf16 v[0:15], v[122:125], v[68:71], v[0:15]
	ds_write2_b32 v32, v36, v52 offset0:32 offset1:64
	ds_write2_b32 v32, v37, v53 offset0:164 offset1:196
	v_add_u32_e32 v32, 0x1400, v92
	ds_write2_b32 v32, v38, v54 offset0:40 offset1:72
	ds_write2_b32 v32, v39, v55 offset0:172 offset1:204
	v_add_u32_e32 v32, 0x2000, v92
	ds_write2_b32 v32, v40, v56 offset0:64 offset1:96
	ds_write2_b32 v32, v41, v57 offset0:196 offset1:228
	v_add_u32_e32 v32, 0x2400, v92
	ds_write2_b32 v32, v42, v58 offset0:72 offset1:104
	ds_write2_b32 v32, v43, v59 offset0:204 offset1:236
	v_mfma_f32_32x32x16_bf16 v[16:31], v[122:125], v[118:121], v[16:31]
	v_add_u32_e32 v32, 0x3000, v92
	ds_write2_b32 v32, v44, v60 offset0:96 offset1:128
	v_add_u32_e32 v32, 0x3200, v92
	ds_write2_b32 v32, v45, v61 offset0:100 offset1:132
	v_add_u32_e32 v32, 0x3400, v92
	ds_write2_b32 v32, v46, v62 offset0:104 offset1:136
	v_add_u32_e32 v32, 0x3600, v92
	ds_write2_b32 v32, v47, v63 offset0:108 offset1:140
	v_add_u32_e32 v32, 0x4000, v92
	s_nop 2
	ds_write2_b32 v32, v0, v16 offset0:128 offset1:160
	v_add_u32_e32 v0, 0x4400, v92
	ds_write2_b32 v0, v1, v17 offset0:4 offset1:36
	ds_write2_b32 v0, v2, v18 offset0:136 offset1:168
	v_add_u32_e32 v0, 0x4800, v92
	ds_write2_b32 v0, v3, v19 offset0:12 offset1:44
	v_add_u32_e32 v0, 0x5000, v92
	ds_write2_b32 v0, v4, v20 offset0:160 offset1:192
	v_add_u32_e32 v0, 0x5400, v92
	ds_write2_b32 v0, v5, v21 offset0:36 offset1:68
	ds_write2_b32 v0, v6, v22 offset0:168 offset1:200
	v_add_u32_e32 v0, 0x5800, v92
	ds_write2_b32 v0, v7, v23 offset0:44 offset1:76
	v_add_u32_e32 v0, 0x6000, v92
	ds_write2_b32 v0, v8, v24 offset0:192 offset1:224
	v_add_u32_e32 v0, 0x6400, v92
	ds_write2_b32 v0, v9, v25 offset0:68 offset1:100
	ds_write2_b32 v0, v10, v26 offset0:200 offset1:232
	v_add_u32_e32 v0, 0x6800, v92
	ds_write2_b32 v0, v11, v27 offset0:76 offset1:108
	v_add_u32_e32 v0, 0x7200, v92
	ds_write2_b32 v0, v12, v28 offset0:96 offset1:128
	v_add_u32_e32 v0, 0x7400, v92
	ds_write2_b32 v0, v13, v29 offset0:100 offset1:132
	v_add_u32_e32 v0, 0x7600, v92
	ds_write2_b32 v0, v14, v30 offset0:104 offset1:136
	v_add_u32_e32 v0, 0x7800, v92
	ds_write2_b32 v0, v15, v31 offset0:108 offset1:140
	v_or_b32_e32 v0, s4, v93
	v_lshlrev_b32_e32 v72, 2, v0
	v_lshl_add_u64 v[4:5], s[38:39], 0, v[72:73]
	v_lshlrev_b32_e32 v72, 1, v0
	v_or_b32_e32 v64, s5, v94
	v_or_b32_e32 v66, s5, v97
	v_or_b32_e32 v68, s5, v103
	v_or_b32_e32 v70, s5, v147
	v_lshl_add_u64 v[6:7], s[20:21], 0, v[72:73]
	global_load_dwordx4 v[240:243], v[4:5], off
	s_waitcnt lgkmcnt(0)
	s_barrier
	s_waitcnt vmcnt(0)
.LBB0_302:
	v_mov_b32_e32 v12, v240
	v_mov_b32_e32 v13, v241
	v_mov_b32_e32 v14, v242
	v_mov_b32_e32 v15, v243
	v_add_u32_e32 v0, s6, v109
	ds_read_b128 v[8:11], v0
	v_ashrrev_i32_e32 v71, 31, v70
	v_ashrrev_i32_e32 v69, 31, v68
	v_ashrrev_i32_e32 v67, 31, v66
	v_ashrrev_i32_e32 v65, 31, v64
	s_waitcnt lgkmcnt(0)
	v_add_f32_e32 v0, v8, v12
	v_mul_f32_e32 v1, 0xbfb8aa3b, v0
	v_exp_f32_e32 v1, v1
	s_nop 0
	v_add_f32_e32 v1, 1.0, v1
	v_rcp_f32_e32 v1, v1
	s_nop 0
	s_nop 0
	s_nop 1
	s_nop 0
	s_nop 1
	v_mul_f32_e32 v0, 0x3f1b4598, v1
	v_add_f32_e32 v1, v9, v13
	v_mul_f32_e32 v2, 0xbfb8aa3b, v1
	v_exp_f32_e32 v2, v2
	s_nop 0
	v_add_f32_e32 v2, 1.0, v2
	v_rcp_f32_e32 v2, v2
	s_nop 0
	s_nop 1
	s_nop 0
	s_nop 1
	v_mul_f32_e32 v1, 0x3f1b4598, v2
	v_mov_b32_e32 v2, v1
	v_add_f32_e32 v1, v10, v14
	v_mul_f32_e32 v3, 0xbfb8aa3b, v1
	v_exp_f32_e32 v3, v3
	s_nop 0
	v_add_f32_e32 v3, 1.0, v3
	v_rcp_f32_e32 v3, v3
	s_nop 0
	s_nop 0
	s_nop 1
	s_nop 0
	s_nop 1
	v_mul_f32_e32 v1, 0x3f1b4598, v3
	v_add_f32_e32 v3, v11, v15
	v_mul_f32_e32 v8, 0xbfb8aa3b, v3
	v_exp_f32_e32 v8, v8
	s_nop 0
	v_add_f32_e32 v8, 1.0, v8
	v_rcp_f32_e32 v8, v8
	s_nop 0
	v_pk_add_f32 v[0:1], v[0:1], 0 neg_lo:[1,1] neg_hi:[1,1]
	s_nop 0
	v_and_b32_sdwa v10, v1, v115 dst_sel:DWORD dst_unused:UNUSED_PAD src0_sel:WORD_1 src1_sel:DWORD
	v_and_b32_sdwa v11, v0, v115 dst_sel:DWORD dst_unused:UNUSED_PAD src0_sel:WORD_1 src1_sel:DWORD
	v_add3_u32 v0, v0, v11, s82
	v_add3_u32 v1, v1, v10, s82
	s_nop 0
	v_mul_f32_e32 v3, 0x3f1b4598, v8
	v_lshlrev_b64 v[8:9], 10, v[70:71]
	v_lshl_add_u64 v[8:9], v[6:7], 0, v[8:9]
	v_add_u32_e32 v70, 32, v70
	v_pk_add_f32 v[2:3], v[2:3], 0 neg_lo:[1,1] neg_hi:[1,1]
	s_nop 0
	v_and_b32_sdwa v10, v3, v115 dst_sel:DWORD dst_unused:UNUSED_PAD src0_sel:WORD_1 src1_sel:DWORD
	v_and_b32_sdwa v11, v2, v115 dst_sel:DWORD dst_unused:UNUSED_PAD src0_sel:WORD_1 src1_sel:DWORD
	v_add3_u32 v3, v3, v10, s82
	v_add3_u32 v2, v2, v11, s82
	v_and_b32_e32 v3, 0xffff0000, v3
	v_and_b32_e32 v2, 0xffff0000, v2
	v_or_b32_sdwa v1, v3, v1 dst_sel:DWORD dst_unused:UNUSED_PAD src0_sel:DWORD src1_sel:WORD_1
	v_or_b32_sdwa v0, v2, v0 dst_sel:DWORD dst_unused:UNUSED_PAD src0_sel:DWORD src1_sel:WORD_1
	global_store_dwordx2 v[8:9], v[0:1], off
	v_mov_b32_e32 v12, v240
	v_mov_b32_e32 v13, v241
	v_mov_b32_e32 v14, v242
	v_mov_b32_e32 v15, v243
	v_add_u32_e32 v0, s6, v108
	ds_read_b128 v[8:11], v0
	s_waitcnt lgkmcnt(0)
	v_add_f32_e32 v0, v8, v12
	v_mul_f32_e32 v1, 0xbfb8aa3b, v0
	v_exp_f32_e32 v1, v1
	s_nop 0
	v_add_f32_e32 v1, 1.0, v1
	v_rcp_f32_e32 v1, v1
	s_nop 0
	s_nop 0
	s_nop 1
	s_nop 0
	s_nop 1
	v_mul_f32_e32 v0, 0x3f1b4598, v1
	v_add_f32_e32 v1, v9, v13
	v_mul_f32_e32 v2, 0xbfb8aa3b, v1
	v_exp_f32_e32 v2, v2
	s_nop 0
	v_add_f32_e32 v2, 1.0, v2
	v_rcp_f32_e32 v2, v2
	s_nop 0
	s_nop 1
	s_nop 0
	s_nop 1
	v_mul_f32_e32 v1, 0x3f1b4598, v2
	v_mov_b32_e32 v2, v1
	v_add_f32_e32 v1, v10, v14
	v_mul_f32_e32 v3, 0xbfb8aa3b, v1
	v_exp_f32_e32 v3, v3
	s_nop 0
	v_add_f32_e32 v3, 1.0, v3
	v_rcp_f32_e32 v3, v3
	s_nop 0
	s_nop 0
	s_nop 1
	s_nop 0
	s_nop 1
	v_mul_f32_e32 v1, 0x3f1b4598, v3
	v_add_f32_e32 v3, v11, v15
	v_mul_f32_e32 v8, 0xbfb8aa3b, v3
	v_exp_f32_e32 v8, v8
	s_nop 0
	v_add_f32_e32 v8, 1.0, v8
	v_rcp_f32_e32 v8, v8
	s_nop 0
	v_pk_add_f32 v[0:1], v[0:1], 0 neg_lo:[1,1] neg_hi:[1,1]
	s_nop 0
	v_and_b32_sdwa v10, v1, v115 dst_sel:DWORD dst_unused:UNUSED_PAD src0_sel:WORD_1 src1_sel:DWORD
	v_and_b32_sdwa v11, v0, v115 dst_sel:DWORD dst_unused:UNUSED_PAD src0_sel:WORD_1 src1_sel:DWORD
	v_add3_u32 v0, v0, v11, s82
	v_add3_u32 v1, v1, v10, s82
	s_nop 0
	v_mul_f32_e32 v3, 0x3f1b4598, v8
	v_lshlrev_b64 v[8:9], 10, v[68:69]
	v_lshl_add_u64 v[8:9], v[6:7], 0, v[8:9]
	v_add_u32_e32 v68, 32, v68
	v_pk_add_f32 v[2:3], v[2:3], 0 neg_lo:[1,1] neg_hi:[1,1]
	s_nop 0
	v_and_b32_sdwa v10, v3, v115 dst_sel:DWORD dst_unused:UNUSED_PAD src0_sel:WORD_1 src1_sel:DWORD
	v_and_b32_sdwa v11, v2, v115 dst_sel:DWORD dst_unused:UNUSED_PAD src0_sel:WORD_1 src1_sel:DWORD
	v_add3_u32 v3, v3, v10, s82
	v_add3_u32 v2, v2, v11, s82
	v_and_b32_e32 v3, 0xffff0000, v3
	v_and_b32_e32 v2, 0xffff0000, v2
	v_or_b32_sdwa v1, v3, v1 dst_sel:DWORD dst_unused:UNUSED_PAD src0_sel:DWORD src1_sel:WORD_1
	v_or_b32_sdwa v0, v2, v0 dst_sel:DWORD dst_unused:UNUSED_PAD src0_sel:DWORD src1_sel:WORD_1
	global_store_dwordx2 v[8:9], v[0:1], off
	v_mov_b32_e32 v12, v240
	v_mov_b32_e32 v13, v241
	v_mov_b32_e32 v14, v242
	v_mov_b32_e32 v15, v243
	v_add_u32_e32 v0, s6, v99
	ds_read_b128 v[8:11], v0
	s_waitcnt lgkmcnt(0)
	v_add_f32_e32 v0, v8, v12
	v_mul_f32_e32 v1, 0xbfb8aa3b, v0
	v_exp_f32_e32 v1, v1
	s_nop 0
	v_add_f32_e32 v1, 1.0, v1
	v_rcp_f32_e32 v1, v1
	s_nop 0
	s_nop 0
	s_nop 1
	s_nop 0
	s_nop 1
	v_mul_f32_e32 v0, 0x3f1b4598, v1
	v_add_f32_e32 v1, v9, v13
	v_mul_f32_e32 v2, 0xbfb8aa3b, v1
	v_exp_f32_e32 v2, v2
	s_nop 0
	v_add_f32_e32 v2, 1.0, v2
	v_rcp_f32_e32 v2, v2
	s_nop 0
	s_nop 1
	s_nop 0
	s_nop 1
	v_mul_f32_e32 v1, 0x3f1b4598, v2
	v_mov_b32_e32 v2, v1
	v_add_f32_e32 v1, v10, v14
	v_mul_f32_e32 v3, 0xbfb8aa3b, v1
	v_exp_f32_e32 v3, v3
	s_nop 0
	v_add_f32_e32 v3, 1.0, v3
	v_rcp_f32_e32 v3, v3
	s_nop 0
	s_nop 0
	s_nop 1
	s_nop 0
	s_nop 1
	v_mul_f32_e32 v1, 0x3f1b4598, v3
	v_add_f32_e32 v3, v11, v15
	v_mul_f32_e32 v8, 0xbfb8aa3b, v3
	v_exp_f32_e32 v8, v8
	s_nop 0
	v_add_f32_e32 v8, 1.0, v8
	v_rcp_f32_e32 v8, v8
	s_nop 0
	v_pk_add_f32 v[0:1], v[0:1], 0 neg_lo:[1,1] neg_hi:[1,1]
	s_nop 0
	v_and_b32_sdwa v10, v1, v115 dst_sel:DWORD dst_unused:UNUSED_PAD src0_sel:WORD_1 src1_sel:DWORD
	v_and_b32_sdwa v11, v0, v115 dst_sel:DWORD dst_unused:UNUSED_PAD src0_sel:WORD_1 src1_sel:DWORD
	v_add3_u32 v0, v0, v11, s82
	v_add3_u32 v1, v1, v10, s82
	s_nop 0
	v_mul_f32_e32 v3, 0x3f1b4598, v8
	v_lshlrev_b64 v[8:9], 10, v[66:67]
	v_lshl_add_u64 v[8:9], v[6:7], 0, v[8:9]
	v_add_u32_e32 v66, 32, v66
	v_pk_add_f32 v[2:3], v[2:3], 0 neg_lo:[1,1] neg_hi:[1,1]
	s_nop 0
	v_and_b32_sdwa v10, v3, v115 dst_sel:DWORD dst_unused:UNUSED_PAD src0_sel:WORD_1 src1_sel:DWORD
	v_and_b32_sdwa v11, v2, v115 dst_sel:DWORD dst_unused:UNUSED_PAD src0_sel:WORD_1 src1_sel:DWORD
	v_add3_u32 v3, v3, v10, s82
	v_add3_u32 v2, v2, v11, s82
	v_and_b32_e32 v3, 0xffff0000, v3
	v_and_b32_e32 v2, 0xffff0000, v2
	v_or_b32_sdwa v1, v3, v1 dst_sel:DWORD dst_unused:UNUSED_PAD src0_sel:DWORD src1_sel:WORD_1
	v_or_b32_sdwa v0, v2, v0 dst_sel:DWORD dst_unused:UNUSED_PAD src0_sel:DWORD src1_sel:WORD_1
	global_store_dwordx2 v[8:9], v[0:1], off
	v_mov_b32_e32 v8, v240
	v_mov_b32_e32 v9, v241
	v_mov_b32_e32 v10, v242
	v_mov_b32_e32 v11, v243
	v_add_u32_e32 v0, s6, v95
	ds_read_b128 v[0:3], v0
	s_addk_i32 s6, 0x4200
	s_cmp_lg_u32 s6, 0x10800
	s_waitcnt lgkmcnt(0)
	v_add_f32_e32 v0, v0, v8
	v_mul_f32_e32 v8, 0xbfb8aa3b, v0
	v_exp_f32_e32 v8, v8
	s_nop 0
	v_add_f32_e32 v8, 1.0, v8
	v_rcp_f32_e32 v8, v8
	s_nop 0
	v_add_f32_e32 v1, v1, v9
	s_nop 1
	s_nop 0
	s_nop 1
	v_mul_f32_e32 v0, 0x3f1b4598, v8
	v_mul_f32_e32 v8, 0xbfb8aa3b, v1
	v_exp_f32_e32 v8, v8
	s_nop 0
	v_add_f32_e32 v8, 1.0, v8
	v_rcp_f32_e32 v8, v8
	s_nop 0
	s_nop 1
	s_nop 0
	s_nop 1
	v_mul_f32_e32 v1, 0x3f1b4598, v8
	v_mov_b32_e32 v8, v1
	v_add_f32_e32 v1, v2, v10
	v_mul_f32_e32 v2, 0xbfb8aa3b, v1
	v_exp_f32_e32 v2, v2
	s_nop 0
	v_add_f32_e32 v2, 1.0, v2
	v_rcp_f32_e32 v2, v2
	s_nop 0
	s_nop 0
	s_nop 1
	s_nop 0
	s_nop 1
	v_mul_f32_e32 v1, 0x3f1b4598, v2
	v_add_f32_e32 v2, v3, v11
	v_mul_f32_e32 v3, 0xbfb8aa3b, v2
	v_exp_f32_e32 v3, v3
	s_nop 0
	v_add_f32_e32 v3, 1.0, v3
	v_rcp_f32_e32 v3, v3
	s_nop 0
	v_pk_add_f32 v[0:1], v[0:1], 0 neg_lo:[1,1] neg_hi:[1,1]
	s_nop 0
	v_and_b32_sdwa v10, v1, v115 dst_sel:DWORD dst_unused:UNUSED_PAD src0_sel:WORD_1 src1_sel:DWORD
	v_and_b32_sdwa v11, v0, v115 dst_sel:DWORD dst_unused:UNUSED_PAD src0_sel:WORD_1 src1_sel:DWORD
	v_add3_u32 v0, v0, v11, s82
	v_add3_u32 v1, v1, v10, s82
	s_nop 0
	v_mul_f32_e32 v2, 0x3f1b4598, v3
	v_mov_b32_e32 v9, v2
	v_lshlrev_b64 v[2:3], 10, v[64:65]
	v_lshl_add_u64 v[2:3], v[6:7], 0, v[2:3]
	v_add_u32_e32 v64, 32, v64
	v_pk_add_f32 v[8:9], v[8:9], 0 neg_lo:[1,1] neg_hi:[1,1]
	s_nop 0
	v_and_b32_sdwa v10, v9, v115 dst_sel:DWORD dst_unused:UNUSED_PAD src0_sel:WORD_1 src1_sel:DWORD
	v_and_b32_sdwa v11, v8, v115 dst_sel:DWORD dst_unused:UNUSED_PAD src0_sel:WORD_1 src1_sel:DWORD
	v_add3_u32 v9, v9, v10, s82
	v_add3_u32 v8, v8, v11, s82
	v_and_b32_e32 v9, 0xffff0000, v9
	v_and_b32_e32 v8, 0xffff0000, v8
	v_or_b32_sdwa v1, v9, v1 dst_sel:DWORD dst_unused:UNUSED_PAD src0_sel:DWORD src1_sel:WORD_1
	v_or_b32_sdwa v0, v8, v0 dst_sel:DWORD dst_unused:UNUSED_PAD src0_sel:DWORD src1_sel:WORD_1
	global_store_dwordx2 v[2:3], v[0:1], off
	s_cbranch_scc1 .LBB0_302
	s_add_i32 s0, s0, s33
	s_add_i32 s1, s1, s80
	s_cmpk_lt_i32 s0, 0x220
	s_barrier
	s_cbranch_scc1 .LBB0_277

.LBB0_330:
	s_or_b64 exec, exec, s[6:7]
	s_waitcnt vmcnt(3)
	v_and_b32_e32 v61, 0xffff0000, v57
	v_and_b32_e32 v60, 0xffff0000, v56
	v_lshlrev_b32_e32 v57, 16, v57
	v_lshlrev_b32_e32 v56, 16, v56
	v_pk_add_f32 v[40:41], v[40:41], v[56:57] neg_lo:[0,1] neg_hi:[0,1]
	s_waitcnt vmcnt(1)
	v_mov_b32_e32 v120, v68
	v_mov_b32_e32 v121, v70
	v_pk_fma_f32 v[40:41], v[120:121], v[40:41], v[56:57]
	v_pk_add_f32 v[56:57], v[62:63], v[60:61] neg_lo:[0,1] neg_hi:[0,1]
	v_mov_b32_e32 v70, v69
	v_pk_fma_f32 v[56:57], v[56:57], v[70:71], v[60:61]
	v_and_b32_sdwa v60, v41, v119 dst_sel:DWORD dst_unused:UNUSED_PAD src0_sel:WORD_1 src1_sel:DWORD
	v_and_b32_sdwa v61, v40, v119 dst_sel:DWORD dst_unused:UNUSED_PAD src0_sel:WORD_1 src1_sel:DWORD
	v_add3_u32 v40, v40, v61, s80
	v_add3_u32 v41, v41, v60, s80
	v_and_b32_sdwa v60, v57, v119 dst_sel:DWORD dst_unused:UNUSED_PAD src0_sel:WORD_1 src1_sel:DWORD
	v_and_b32_sdwa v61, v56, v119 dst_sel:DWORD dst_unused:UNUSED_PAD src0_sel:WORD_1 src1_sel:DWORD
	v_add3_u32 v57, v57, v60, s80
	v_add3_u32 v56, v56, v61, s80
	v_and_b32_e32 v33, 0xffff0000, v59
	v_and_b32_e32 v32, 0xffff0000, v58
	v_lshlrev_b32_e32 v59, 16, v59
	v_lshlrev_b32_e32 v58, 16, v58
	v_and_b32_e32 v57, 0xffff0000, v57
	v_and_b32_e32 v56, 0xffff0000, v56
	v_or_b32_sdwa v41, v57, v41 dst_sel:DWORD dst_unused:UNUSED_PAD src0_sel:DWORD src1_sel:WORD_1
	v_or_b32_sdwa v40, v56, v40 dst_sel:DWORD dst_unused:UNUSED_PAD src0_sel:DWORD src1_sel:WORD_1
	v_pk_add_f32 v[48:49], v[48:49], v[58:59] neg_lo:[0,1] neg_hi:[0,1]
	v_mov_b32_e32 v56, v64
	v_mov_b32_e32 v57, v66
	v_pk_fma_f32 v[48:49], v[48:49], v[56:57], v[58:59]
	v_pk_add_f32 v[42:43], v[42:43], v[32:33] neg_lo:[0,1] neg_hi:[0,1]
	v_mov_b32_e32 v66, v65
	v_pk_fma_f32 v[32:33], v[42:43], v[66:67], v[32:33]
	v_and_b32_sdwa v42, v49, v119 dst_sel:DWORD dst_unused:UNUSED_PAD src0_sel:WORD_1 src1_sel:DWORD
	v_and_b32_sdwa v43, v48, v119 dst_sel:DWORD dst_unused:UNUSED_PAD src0_sel:WORD_1 src1_sel:DWORD
	v_add3_u32 v48, v48, v43, s80
	v_add3_u32 v42, v49, v42, s80
	v_and_b32_sdwa v43, v33, v119 dst_sel:DWORD dst_unused:UNUSED_PAD src0_sel:WORD_1 src1_sel:DWORD
	v_and_b32_sdwa v49, v32, v119 dst_sel:DWORD dst_unused:UNUSED_PAD src0_sel:WORD_1 src1_sel:DWORD
	v_add3_u32 v33, v33, v43, s80
	v_add3_u32 v32, v32, v49, s80
	v_and_b32_e32 v33, 0xffff0000, v33
	v_and_b32_e32 v32, 0xffff0000, v32
	v_or_b32_sdwa v43, v33, v42 dst_sel:DWORD dst_unused:UNUSED_PAD src0_sel:DWORD src1_sel:WORD_1
	v_or_b32_sdwa v42, v32, v48 dst_sel:DWORD dst_unused:UNUSED_PAD src0_sel:DWORD src1_sel:WORD_1
	v_and_b32_e32 v49, 0xffff0000, v45
	v_and_b32_e32 v48, 0xffff0000, v44
	v_lshlrev_b32_e32 v45, 16, v45
	v_lshlrev_b32_e32 v44, 16, v44
	v_pk_add_f32 v[20:21], v[20:21], v[44:45] neg_lo:[0,1] neg_hi:[0,1]
	v_mov_b32_e32 v56, v52
	v_mov_b32_e32 v57, v54
	v_pk_fma_f32 v[20:21], v[56:57], v[20:21], v[44:45]
	v_pk_add_f32 v[44:45], v[50:51], v[48:49] neg_lo:[0,1] neg_hi:[0,1]
	v_mov_b32_e32 v54, v53
	v_pk_fma_f32 v[44:45], v[44:45], v[54:55], v[48:49]
	v_and_b32_sdwa v48, v21, v119 dst_sel:DWORD dst_unused:UNUSED_PAD src0_sel:WORD_1 src1_sel:DWORD
	v_and_b32_sdwa v49, v20, v119 dst_sel:DWORD dst_unused:UNUSED_PAD src0_sel:WORD_1 src1_sel:DWORD
	v_add3_u32 v20, v20, v49, s80
	v_add3_u32 v21, v21, v48, s80
	v_and_b32_sdwa v48, v45, v119 dst_sel:DWORD dst_unused:UNUSED_PAD src0_sel:WORD_1 src1_sel:DWORD
	v_and_b32_sdwa v49, v44, v119 dst_sel:DWORD dst_unused:UNUSED_PAD src0_sel:WORD_1 src1_sel:DWORD
	v_add3_u32 v45, v45, v48, s80
	v_add3_u32 v44, v44, v49, s80
	v_and_b32_e32 v33, 0xffff0000, v47
	v_and_b32_e32 v32, 0xffff0000, v46
	v_lshlrev_b32_e32 v47, 16, v47
	v_lshlrev_b32_e32 v46, 16, v46
	v_and_b32_e32 v45, 0xffff0000, v45
	v_and_b32_e32 v44, 0xffff0000, v44
	v_or_b32_sdwa v21, v45, v21 dst_sel:DWORD dst_unused:UNUSED_PAD src0_sel:DWORD src1_sel:WORD_1
	v_or_b32_sdwa v20, v44, v20 dst_sel:DWORD dst_unused:UNUSED_PAD src0_sel:DWORD src1_sel:WORD_1
	v_pk_add_f32 v[44:45], v[94:95], v[46:47] neg_lo:[0,1] neg_hi:[0,1]
	v_mov_b32_e32 v48, v28
	v_mov_b32_e32 v49, v30
	v_pk_fma_f32 v[48:49], v[44:45], v[48:49], v[46:47]
	global_load_dwordx4 v[44:47], v[82:83], off
	v_pk_add_f32 v[22:23], v[22:23], v[32:33] neg_lo:[0,1] neg_hi:[0,1]
	v_mov_b32_e32 v30, v29
	v_pk_fma_f32 v[22:23], v[22:23], v[30:31], v[32:33]
	v_and_b32_sdwa v28, v49, v119 dst_sel:DWORD dst_unused:UNUSED_PAD src0_sel:WORD_1 src1_sel:DWORD
	v_and_b32_sdwa v30, v23, v119 dst_sel:DWORD dst_unused:UNUSED_PAD src0_sel:WORD_1 src1_sel:DWORD
	v_and_b32_sdwa v31, v22, v119 dst_sel:DWORD dst_unused:UNUSED_PAD src0_sel:WORD_1 src1_sel:DWORD
	v_and_b32_sdwa v29, v48, v119 dst_sel:DWORD dst_unused:UNUSED_PAD src0_sel:WORD_1 src1_sel:DWORD
	v_add3_u32 v23, v23, v30, s80
	v_add3_u32 v22, v22, v31, s80
	v_add3_u32 v29, v48, v29, s80
	v_add3_u32 v28, v49, v28, s80
	v_and_b32_e32 v23, 0xffff0000, v23
	v_and_b32_e32 v22, 0xffff0000, v22
	v_or_b32_sdwa v23, v23, v28 dst_sel:DWORD dst_unused:UNUSED_PAD src0_sel:DWORD src1_sel:WORD_1
	v_or_b32_sdwa v22, v22, v29 dst_sel:DWORD dst_unused:UNUSED_PAD src0_sel:DWORD src1_sel:WORD_1
	global_load_dwordx4 v[28:31], v[82:83], off offset:16
	v_and_b32_e32 v33, 0xffff0000, v3
	v_and_b32_e32 v32, 0xffff0000, v2
	v_lshlrev_b32_e32 v57, 16, v3
	v_lshlrev_b32_e32 v56, 16, v2
	v_and_b32_e32 v3, 0xffff0000, v1
	v_and_b32_e32 v2, 0xffff0000, v0
	v_lshlrev_b32_e32 v1, 16, v1
	v_lshlrev_b32_e32 v0, 16, v0
	v_pk_add_f32 v[4:5], v[4:5], v[0:1] neg_lo:[0,1] neg_hi:[0,1]
	v_mov_b32_e32 v48, v16
	v_mov_b32_e32 v49, v18
	s_lshl_b32 s4, s0, 7
	v_pk_fma_f32 v[0:1], v[48:49], v[4:5], v[0:1]
	v_pk_add_f32 v[4:5], v[10:11], v[2:3] neg_lo:[0,1] neg_hi:[0,1]
	v_mov_b32_e32 v18, v17
	s_and_b32 s4, s4, 0x180
	v_pk_fma_f32 v[2:3], v[4:5], v[18:19], v[2:3]
	v_and_b32_sdwa v4, v1, v119 dst_sel:DWORD dst_unused:UNUSED_PAD src0_sel:WORD_1 src1_sel:DWORD
	v_and_b32_sdwa v5, v0, v119 dst_sel:DWORD dst_unused:UNUSED_PAD src0_sel:WORD_1 src1_sel:DWORD
	v_add_lshl_u32 v72, s4, v105, 7
	v_add3_u32 v10, v0, v5, s80
	v_add3_u32 v11, v1, v4, s80
	v_and_b32_sdwa v0, v3, v119 dst_sel:DWORD dst_unused:UNUSED_PAD src0_sel:WORD_1 src1_sel:DWORD
	v_and_b32_sdwa v1, v2, v119 dst_sel:DWORD dst_unused:UNUSED_PAD src0_sel:WORD_1 src1_sel:DWORD
	v_lshl_add_u64 v[4:5], v[84:85], 0, v[72:73]
	v_add3_u32 v58, v3, v0, s80
	v_add3_u32 v59, v2, v1, s80
	global_load_dwordx4 v[0:3], v[4:5], off
	global_load_dwordx4 v[16:19], v[4:5], off offset:16
	global_load_dwordx4 v[48:51], v[4:5], off offset:32
	global_load_dwordx4 v[52:55], v[4:5], off offset:48
	v_and_b32_e32 v4, 0xffff0000, v58
	v_and_b32_e32 v58, 0xffff0000, v59
	v_or_b32_sdwa v5, v4, v11 dst_sel:DWORD dst_unused:UNUSED_PAD src0_sel:DWORD src1_sel:WORD_1
	v_or_b32_sdwa v4, v58, v10 dst_sel:DWORD dst_unused:UNUSED_PAD src0_sel:DWORD src1_sel:WORD_1
	v_pk_add_f32 v[10:11], v[92:93], v[56:57] neg_lo:[0,1] neg_hi:[0,1]
	v_mov_b32_e32 v58, v12
	v_mov_b32_e32 v59, v14
	v_pk_fma_f32 v[10:11], v[10:11], v[58:59], v[56:57]
	v_pk_add_f32 v[6:7], v[6:7], v[32:33] neg_lo:[0,1] neg_hi:[0,1]
	v_mov_b32_e32 v14, v13
	v_pk_fma_f32 v[6:7], v[6:7], v[14:15], v[32:33]
	v_and_b32_sdwa v12, v11, v119 dst_sel:DWORD dst_unused:UNUSED_PAD src0_sel:WORD_1 src1_sel:DWORD
	v_and_b32_sdwa v13, v10, v119 dst_sel:DWORD dst_unused:UNUSED_PAD src0_sel:WORD_1 src1_sel:DWORD
	v_add3_u32 v10, v10, v13, s80
	v_add3_u32 v11, v11, v12, s80
	v_and_b32_sdwa v12, v7, v119 dst_sel:DWORD dst_unused:UNUSED_PAD src0_sel:WORD_1 src1_sel:DWORD
	v_and_b32_sdwa v13, v6, v119 dst_sel:DWORD dst_unused:UNUSED_PAD src0_sel:WORD_1 src1_sel:DWORD
	v_add3_u32 v7, v7, v12, s80
	v_add3_u32 v6, v6, v13, s80
	v_and_b32_e32 v7, 0xffff0000, v7
	v_and_b32_e32 v6, 0xffff0000, v6
	s_waitcnt vmcnt(6)
	v_lshlrev_b32_e32 v33, 16, v37
	v_lshlrev_b32_e32 v32, 16, v36
	v_or_b32_sdwa v7, v7, v11 dst_sel:DWORD dst_unused:UNUSED_PAD src0_sel:DWORD src1_sel:WORD_1
	v_or_b32_sdwa v6, v6, v10 dst_sel:DWORD dst_unused:UNUSED_PAD src0_sel:DWORD src1_sel:WORD_1
	v_and_b32_e32 v11, 0xffff0000, v37
	v_and_b32_e32 v10, 0xffff0000, v36
	v_pk_add_f32 v[24:25], v[24:25], v[32:33] neg_lo:[0,1] neg_hi:[0,1]
	v_lshlrev_b32_e32 v15, 16, v39
	v_lshlrev_b32_e32 v14, 16, v38
	v_and_b32_e32 v13, 0xffff0000, v39
	v_and_b32_e32 v12, 0xffff0000, v38
	v_pk_add_f32 v[8:9], v[8:9], v[14:15] neg_lo:[0,1] neg_hi:[0,1]
	s_barrier
	s_waitcnt vmcnt(5)
	v_mov_b32_e32 v36, v44
	v_mov_b32_e32 v37, v46
	v_pk_fma_f32 v[24:25], v[36:37], v[24:25], v[32:33]
	v_pk_add_f32 v[32:33], v[34:35], v[10:11] neg_lo:[0,1] neg_hi:[0,1]
	v_mov_b32_e32 v46, v45
	v_pk_fma_f32 v[10:11], v[32:33], v[46:47], v[10:11]
	v_and_b32_sdwa v32, v25, v119 dst_sel:DWORD dst_unused:UNUSED_PAD src0_sel:WORD_1 src1_sel:DWORD
	v_and_b32_sdwa v33, v24, v119 dst_sel:DWORD dst_unused:UNUSED_PAD src0_sel:WORD_1 src1_sel:DWORD
	v_add3_u32 v24, v24, v33, s80
	v_add3_u32 v25, v25, v32, s80
	v_and_b32_sdwa v32, v11, v119 dst_sel:DWORD dst_unused:UNUSED_PAD src0_sel:WORD_1 src1_sel:DWORD
	v_and_b32_sdwa v33, v10, v119 dst_sel:DWORD dst_unused:UNUSED_PAD src0_sel:WORD_1 src1_sel:DWORD
	v_add3_u32 v11, v11, v32, s80
	v_add3_u32 v10, v10, v33, s80
	v_and_b32_e32 v11, 0xffff0000, v11
	v_and_b32_e32 v10, 0xffff0000, v10
	v_or_b32_sdwa v11, v11, v25 dst_sel:DWORD dst_unused:UNUSED_PAD src0_sel:DWORD src1_sel:WORD_1
	v_or_b32_sdwa v10, v10, v24 dst_sel:DWORD dst_unused:UNUSED_PAD src0_sel:DWORD src1_sel:WORD_1
	s_waitcnt vmcnt(4)
	v_mov_b32_e32 v24, v28
	v_mov_b32_e32 v25, v30
	v_pk_fma_f32 v[8:9], v[8:9], v[24:25], v[14:15]
	v_pk_add_f32 v[14:15], v[26:27], v[12:13] neg_lo:[0,1] neg_hi:[0,1]
	v_mov_b32_e32 v30, v29
	v_pk_fma_f32 v[12:13], v[14:15], v[30:31], v[12:13]
	v_and_b32_sdwa v14, v9, v119 dst_sel:DWORD dst_unused:UNUSED_PAD src0_sel:WORD_1 src1_sel:DWORD
	v_and_b32_sdwa v15, v8, v119 dst_sel:DWORD dst_unused:UNUSED_PAD src0_sel:WORD_1 src1_sel:DWORD
	v_add3_u32 v8, v8, v15, s80
	v_add3_u32 v9, v9, v14, s80
	v_and_b32_sdwa v14, v13, v119 dst_sel:DWORD dst_unused:UNUSED_PAD src0_sel:WORD_1 src1_sel:DWORD
	v_and_b32_sdwa v15, v12, v119 dst_sel:DWORD dst_unused:UNUSED_PAD src0_sel:WORD_1 src1_sel:DWORD
	v_add3_u32 v13, v13, v14, s80
	v_add3_u32 v12, v12, v15, s80
	v_and_b32_e32 v13, 0xffff0000, v13
	v_and_b32_e32 v12, 0xffff0000, v12
	v_or_b32_sdwa v13, v13, v9 dst_sel:DWORD dst_unused:UNUSED_PAD src0_sel:DWORD src1_sel:WORD_1
	v_or_b32_sdwa v12, v12, v8 dst_sel:DWORD dst_unused:UNUSED_PAD src0_sel:DWORD src1_sel:WORD_1
	ds_write_b128 v116, v[4:7]
	ds_write_b128 v116, v[20:23] offset:16
	ds_write_b128 v116, v[40:43] offset:32
	ds_write_b128 v116, v[10:13] offset:48
	s_waitcnt vmcnt(3)
	ds_write_b128 v116, v[0:3] offset:18432
	s_waitcnt vmcnt(2)
	ds_write_b128 v116, v[16:19] offset:18448
	s_waitcnt vmcnt(1)
	ds_write_b128 v116, v[48:51] offset:18464
	s_waitcnt vmcnt(0)
	ds_write_b128 v116, v[52:55] offset:18480
	s_waitcnt lgkmcnt(0)
	s_barrier
	ds_read_b128 v[0:3], v117
	ds_read_b128 v[4:7], v118 offset:18432
	ds_read_b128 v[16:19], v118 offset:23040
	ds_read_b128 v[20:23], v117 offset:4608
	s_waitcnt lgkmcnt(2)
	v_mfma_f32_32x32x16_bf16 v[32:47], v[0:3], v[4:7], 0
	ds_read_b128 v[64:67], v117 offset:32
	ds_read_b128 v[68:71], v118 offset:18464
	ds_read_b128 v[92:95], v118 offset:23072
	v_readlane_b32 s36, v236, 48
	v_readlane_b32 s42, v236, 54
	v_readlane_b32 s43, v236, 55
	v_readlane_b32 s16, v238, 32
	s_and_b32 s5, s1, 0xffffff80
	s_waitcnt lgkmcnt(4)
	v_mfma_f32_32x32x16_bf16 v[48:63], v[0:3], v[16:19], 0
	v_readlane_b32 s22, v238, 38
	v_readlane_b32 s23, v238, 39
	v_readlane_b32 s37, v236, 49
	v_readlane_b32 s38, v236, 50
	v_readlane_b32 s39, v236, 51
	v_readlane_b32 s40, v236, 52
	v_readlane_b32 s41, v236, 53
	s_waitcnt lgkmcnt(1)
	v_mfma_f32_32x32x16_bf16 v[32:47], v[64:67], v[68:71], v[32:47]
	v_readlane_b32 s44, v236, 56
	v_readlane_b32 s45, v236, 57
	v_readlane_b32 s46, v236, 58
	v_readlane_b32 s47, v236, 59
	v_readlane_b32 s48, v236, 60
	v_readlane_b32 s49, v236, 61
	v_readlane_b32 s50, v236, 62
	s_waitcnt lgkmcnt(0)
	v_mfma_f32_32x32x16_bf16 v[48:63], v[64:67], v[92:95], v[48:63]
	ds_read_b128 v[64:67], v117 offset:4640
	v_readlane_b32 s51, v236, 63
	v_readlane_b32 s17, v238, 33
	v_readlane_b32 s18, v238, 34
	v_readlane_b32 s19, v238, 35
	v_readlane_b32 s20, v238, 36
	v_readlane_b32 s21, v238, 37
	v_mfma_f32_32x32x16_bf16 v[0:15], v[20:23], v[4:7], 0
	v_readlane_b32 s24, v238, 40
	v_readlane_b32 s25, v238, 41
	v_readlane_b32 s26, v238, 42
	v_readlane_b32 s27, v238, 43
	v_readlane_b32 s28, v238, 44
	v_readlane_b32 s29, v238, 45
	v_readlane_b32 s30, v238, 46
	v_mfma_f32_32x32x16_bf16 v[16:31], v[20:23], v[16:19], 0
	v_readlane_b32 s31, v238, 47
	s_waitcnt lgkmcnt(0)
	v_mfma_f32_32x32x16_bf16 v[0:15], v[64:67], v[68:71], v[0:15]
	v_mfma_f32_32x32x16_bf16 v[16:31], v[64:67], v[92:95], v[16:31]
	ds_read_b128 v[64:67], v117 offset:64
	ds_read_b128 v[68:71], v118 offset:18496
	ds_read_b128 v[92:95], v118 offset:23104
	s_waitcnt lgkmcnt(1)
	v_mfma_f32_32x32x16_bf16 v[32:47], v[64:67], v[68:71], v[32:47]
	s_waitcnt lgkmcnt(0)
	v_mfma_f32_32x32x16_bf16 v[48:63], v[64:67], v[92:95], v[48:63]
	ds_read_b128 v[64:67], v117 offset:4672
	s_waitcnt lgkmcnt(0)
	v_mfma_f32_32x32x16_bf16 v[0:15], v[64:67], v[68:71], v[0:15]
	v_mfma_f32_32x32x16_bf16 v[16:31], v[64:67], v[92:95], v[16:31]
	ds_read_b128 v[64:67], v117 offset:96
	ds_read_b128 v[68:71], v118 offset:18528
	ds_read_b128 v[92:95], v118 offset:23136
	ds_read_b128 v[120:123], v117 offset:4704
	s_waitcnt lgkmcnt(0)
	s_barrier
	v_mfma_f32_32x32x16_bf16 v[32:47], v[64:67], v[68:71], v[32:47]
	v_mfma_f32_32x32x16_bf16 v[48:63], v[64:67], v[92:95], v[48:63]
	s_nop 11
	ds_write2_b32 v97, v32, v48 offset1:32
	ds_write2_b32 v97, v33, v49 offset0:132 offset1:164
	v_add_u32_e32 v32, 0x400, v97
	ds_write2_b32 v32, v34, v50 offset0:8 offset1:40
	ds_write2_b32 v32, v35, v51 offset0:140 offset1:172
	v_add_u32_e32 v32, 0x1000, v97
	v_mfma_f32_32x32x16_bf16 v[0:15], v[120:123], v[68:71], v[0:15]
	ds_write2_b32 v32, v36, v52 offset0:32 offset1:64
	ds_write2_b32 v32, v37, v53 offset0:164 offset1:196
	v_add_u32_e32 v32, 0x1400, v97
	ds_write2_b32 v32, v38, v54 offset0:40 offset1:72
	ds_write2_b32 v32, v39, v55 offset0:172 offset1:204
	v_add_u32_e32 v32, 0x2000, v97
	ds_write2_b32 v32, v40, v56 offset0:64 offset1:96
	ds_write2_b32 v32, v41, v57 offset0:196 offset1:228
	v_add_u32_e32 v32, 0x2400, v97
	ds_write2_b32 v32, v42, v58 offset0:72 offset1:104
	ds_write2_b32 v32, v43, v59 offset0:204 offset1:236
	v_mfma_f32_32x32x16_bf16 v[16:31], v[120:123], v[92:95], v[16:31]
	v_add_u32_e32 v32, 0x3000, v97
	ds_write2_b32 v32, v44, v60 offset0:96 offset1:128
	v_add_u32_e32 v32, 0x3200, v97
	ds_write2_b32 v32, v45, v61 offset0:100 offset1:132
	v_add_u32_e32 v32, 0x3400, v97
	ds_write2_b32 v32, v46, v62 offset0:104 offset1:136
	v_add_u32_e32 v32, 0x3600, v97
	ds_write2_b32 v32, v47, v63 offset0:108 offset1:140
	v_add_u32_e32 v32, 0x4000, v97
	s_nop 2
	ds_write2_b32 v32, v0, v16 offset0:128 offset1:160
	v_add_u32_e32 v0, 0x4400, v97
	ds_write2_b32 v0, v1, v17 offset0:4 offset1:36
	ds_write2_b32 v0, v2, v18 offset0:136 offset1:168
	v_add_u32_e32 v0, 0x4800, v97
	ds_write2_b32 v0, v3, v19 offset0:12 offset1:44
	v_add_u32_e32 v0, 0x5000, v97
	ds_write2_b32 v0, v4, v20 offset0:160 offset1:192
	v_add_u32_e32 v0, 0x5400, v97
	ds_write2_b32 v0, v5, v21 offset0:36 offset1:68
	ds_write2_b32 v0, v6, v22 offset0:168 offset1:200
	v_add_u32_e32 v0, 0x5800, v97
	ds_write2_b32 v0, v7, v23 offset0:44 offset1:76
	v_add_u32_e32 v0, 0x6000, v97
	ds_write2_b32 v0, v8, v24 offset0:192 offset1:224
	v_add_u32_e32 v0, 0x6400, v97
	ds_write2_b32 v0, v9, v25 offset0:68 offset1:100
	ds_write2_b32 v0, v10, v26 offset0:200 offset1:232
	v_add_u32_e32 v0, 0x6800, v97
	ds_write2_b32 v0, v11, v27 offset0:76 offset1:108
	v_add_u32_e32 v0, 0x7200, v97
	ds_write2_b32 v0, v12, v28 offset0:96 offset1:128
	v_add_u32_e32 v0, 0x7400, v97
	ds_write2_b32 v0, v13, v29 offset0:100 offset1:132
	v_add_u32_e32 v0, 0x7600, v97
	ds_write2_b32 v0, v14, v30 offset0:104 offset1:136
	v_add_u32_e32 v0, 0x7800, v97
	ds_write2_b32 v0, v15, v31 offset0:108 offset1:140
	v_or_b32_e32 v0, s4, v99
	v_lshlrev_b32_e32 v72, 2, v0
	v_lshl_add_u64 v[4:5], s[42:43], 0, v[72:73]
	v_lshlrev_b32_e32 v72, 1, v0
	v_or_b32_e32 v64, s5, v103
	v_or_b32_e32 v66, s5, v109
	v_or_b32_e32 v68, s5, v112
	v_or_b32_e32 v70, s5, v147
	v_lshl_add_u64 v[6:7], s[22:23], 0, v[72:73]
	s_mov_b32 s4, 0
	global_load_dwordx4 v[240:243], v[4:5], off
	s_waitcnt lgkmcnt(0)
	s_barrier
	s_waitcnt vmcnt(0)
.LBB0_331:
	v_mov_b32_e32 v8, v240
	v_mov_b32_e32 v9, v241
	v_mov_b32_e32 v10, v242
	v_mov_b32_e32 v11, v243
	v_add_u32_e32 v0, s4, v114
	ds_read_b128 v[0:3], v0
	v_ashrrev_i32_e32 v71, 31, v70
	v_ashrrev_i32_e32 v69, 31, v68
	v_ashrrev_i32_e32 v67, 31, v66
	v_ashrrev_i32_e32 v65, 31, v64
	s_waitcnt lgkmcnt(0)
	v_add_f32_e32 v1, v1, v9
	v_mul_f32_e32 v1, 0xbfb8aa3b, v1
	v_add_f32_e32 v0, v0, v8
	v_exp_f32_e32 v8, v1
	v_add_f32_e32 v1, v2, v10
	v_mul_f32_e32 v0, 0xbfb8aa3b, v0
	v_mul_f32_e32 v1, 0xbfb8aa3b, v1
	v_exp_f32_e32 v0, v0
	v_exp_f32_e32 v1, v1
	v_add_f32_e32 v2, v3, v11
	v_mul_f32_e32 v2, 0xbfb8aa3b, v2
	v_exp_f32_e32 v9, v2
	v_pk_add_f32 v[0:1], v[0:1], 1.0 op_sel_hi:[1,0]
	v_lshlrev_b64 v[2:3], 10, v[70:71]
	v_div_scale_f32 v10, s[6:7], v0, v0, 1.0
	v_rcp_f32_e32 v11, v10
	v_lshl_add_u64 v[2:3], v[6:7], 0, v[2:3]
	v_add_u32_e32 v70, 32, v70
	v_fma_f32 v12, -v10, v11, 1.0
	v_fmac_f32_e32 v11, v12, v11
	v_div_scale_f32 v12, vcc, 1.0, v0, 1.0
	v_mul_f32_e32 v13, v12, v11
	v_fma_f32 v14, -v10, v13, v12
	v_fmac_f32_e32 v13, v14, v11
	v_fma_f32 v10, -v10, v13, v12
	v_div_fmas_f32 v10, v10, v11, v13
	v_div_fixup_f32 v10, v10, v0, 1.0
	v_div_scale_f32 v0, s[6:7], v1, v1, 1.0
	v_rcp_f32_e32 v11, v0
	s_nop 0
	v_fma_f32 v12, -v0, v11, 1.0
	v_fmac_f32_e32 v11, v12, v11
	v_div_scale_f32 v12, vcc, 1.0, v1, 1.0
	v_mul_f32_e32 v13, v12, v11
	v_fma_f32 v14, -v0, v13, v12
	v_fmac_f32_e32 v13, v14, v11
	v_fma_f32 v0, -v0, v13, v12
	v_div_fmas_f32 v0, v0, v11, v13
	v_div_fixup_f32 v11, v0, v1, 1.0
	v_pk_add_f32 v[0:1], v[8:9], 1.0 op_sel_hi:[1,0]
	s_nop 0
	v_div_scale_f32 v8, s[6:7], v0, v0, 1.0
	v_rcp_f32_e32 v9, v8
	s_nop 0
	v_fma_f32 v12, -v8, v9, 1.0
	v_fmac_f32_e32 v9, v12, v9
	v_div_scale_f32 v12, vcc, 1.0, v0, 1.0
	v_mul_f32_e32 v13, v12, v9
	v_fma_f32 v14, -v8, v13, v12
	v_fmac_f32_e32 v13, v14, v9
	v_fma_f32 v8, -v8, v13, v12
	v_div_fmas_f32 v8, v8, v9, v13
	v_div_fixup_f32 v0, v8, v0, 1.0
	v_div_scale_f32 v8, s[6:7], v1, v1, 1.0
	v_rcp_f32_e32 v9, v8
	s_nop 0
	v_fma_f32 v12, -v8, v9, 1.0
	v_fmac_f32_e32 v9, v12, v9
	v_div_scale_f32 v12, vcc, 1.0, v1, 1.0
	v_mul_f32_e32 v13, v12, v9
	v_fma_f32 v14, -v8, v13, v12
	v_fmac_f32_e32 v13, v14, v9
	v_fma_f32 v8, -v8, v13, v12
	v_div_fmas_f32 v8, v8, v9, v13
	v_div_fixup_f32 v1, v8, v1, 1.0
	v_and_b32_sdwa v8, v11, v119 dst_sel:DWORD dst_unused:UNUSED_PAD src0_sel:WORD_1 src1_sel:DWORD
	v_and_b32_sdwa v9, v10, v119 dst_sel:DWORD dst_unused:UNUSED_PAD src0_sel:WORD_1 src1_sel:DWORD
	v_add3_u32 v9, v10, v9, s80
	v_add3_u32 v8, v11, v8, s80
	v_and_b32_sdwa v10, v1, v119 dst_sel:DWORD dst_unused:UNUSED_PAD src0_sel:WORD_1 src1_sel:DWORD
	v_and_b32_sdwa v11, v0, v119 dst_sel:DWORD dst_unused:UNUSED_PAD src0_sel:WORD_1 src1_sel:DWORD
	v_add3_u32 v1, v1, v10, s80
	v_add3_u32 v0, v0, v11, s80
	v_and_b32_e32 v1, 0xffff0000, v1
	v_and_b32_e32 v0, 0xffff0000, v0
	v_or_b32_sdwa v1, v1, v8 dst_sel:DWORD dst_unused:UNUSED_PAD src0_sel:DWORD src1_sel:WORD_1
	v_or_b32_sdwa v0, v0, v9 dst_sel:DWORD dst_unused:UNUSED_PAD src0_sel:DWORD src1_sel:WORD_1
	global_store_dwordx2 v[2:3], v[0:1], off
	v_mov_b32_e32 v8, v240
	v_mov_b32_e32 v9, v241
	v_mov_b32_e32 v10, v242
	v_mov_b32_e32 v11, v243
	v_add_u32_e32 v0, s4, v113
	ds_read_b128 v[0:3], v0
	s_waitcnt lgkmcnt(0)
	v_add_f32_e32 v1, v1, v9
	v_mul_f32_e32 v1, 0xbfb8aa3b, v1
	v_add_f32_e32 v0, v0, v8
	v_exp_f32_e32 v8, v1
	v_add_f32_e32 v1, v2, v10
	v_mul_f32_e32 v0, 0xbfb8aa3b, v0
	v_mul_f32_e32 v1, 0xbfb8aa3b, v1
	v_exp_f32_e32 v0, v0
	v_exp_f32_e32 v1, v1
	v_add_f32_e32 v2, v3, v11
	v_mul_f32_e32 v2, 0xbfb8aa3b, v2
	v_exp_f32_e32 v9, v2
	v_pk_add_f32 v[0:1], v[0:1], 1.0 op_sel_hi:[1,0]
	v_lshlrev_b64 v[2:3], 10, v[68:69]
	v_div_scale_f32 v10, s[6:7], v0, v0, 1.0
	v_rcp_f32_e32 v11, v10
	v_lshl_add_u64 v[2:3], v[6:7], 0, v[2:3]
	v_add_u32_e32 v68, 32, v68
	v_fma_f32 v12, -v10, v11, 1.0
	v_fmac_f32_e32 v11, v12, v11
	v_div_scale_f32 v12, vcc, 1.0, v0, 1.0
	v_mul_f32_e32 v13, v12, v11
	v_fma_f32 v14, -v10, v13, v12
	v_fmac_f32_e32 v13, v14, v11
	v_fma_f32 v10, -v10, v13, v12
	v_div_fmas_f32 v10, v10, v11, v13
	v_div_fixup_f32 v10, v10, v0, 1.0
	v_div_scale_f32 v0, s[6:7], v1, v1, 1.0
	v_rcp_f32_e32 v11, v0
	s_nop 0
	v_fma_f32 v12, -v0, v11, 1.0
	v_fmac_f32_e32 v11, v12, v11
	v_div_scale_f32 v12, vcc, 1.0, v1, 1.0
	v_mul_f32_e32 v13, v12, v11
	v_fma_f32 v14, -v0, v13, v12
	v_fmac_f32_e32 v13, v14, v11
	v_fma_f32 v0, -v0, v13, v12
	v_div_fmas_f32 v0, v0, v11, v13
	v_div_fixup_f32 v11, v0, v1, 1.0
	v_pk_add_f32 v[0:1], v[8:9], 1.0 op_sel_hi:[1,0]
	s_nop 0
	v_div_scale_f32 v8, s[6:7], v0, v0, 1.0
	v_rcp_f32_e32 v9, v8
	s_nop 0
	v_fma_f32 v12, -v8, v9, 1.0
	v_fmac_f32_e32 v9, v12, v9
	v_div_scale_f32 v12, vcc, 1.0, v0, 1.0
	v_mul_f32_e32 v13, v12, v9
	v_fma_f32 v14, -v8, v13, v12
	v_fmac_f32_e32 v13, v14, v9
	v_fma_f32 v8, -v8, v13, v12
	v_div_fmas_f32 v8, v8, v9, v13
	v_div_fixup_f32 v0, v8, v0, 1.0
	v_div_scale_f32 v8, s[6:7], v1, v1, 1.0
	v_rcp_f32_e32 v9, v8
	s_nop 0
	v_fma_f32 v12, -v8, v9, 1.0
	v_fmac_f32_e32 v9, v12, v9
	v_div_scale_f32 v12, vcc, 1.0, v1, 1.0
	v_mul_f32_e32 v13, v12, v9
	v_fma_f32 v14, -v8, v13, v12
	v_fmac_f32_e32 v13, v14, v9
	v_fma_f32 v8, -v8, v13, v12
	v_div_fmas_f32 v8, v8, v9, v13
	v_div_fixup_f32 v1, v8, v1, 1.0
	v_and_b32_sdwa v8, v11, v119 dst_sel:DWORD dst_unused:UNUSED_PAD src0_sel:WORD_1 src1_sel:DWORD
	v_and_b32_sdwa v9, v10, v119 dst_sel:DWORD dst_unused:UNUSED_PAD src0_sel:WORD_1 src1_sel:DWORD
	v_add3_u32 v9, v10, v9, s80
	v_add3_u32 v8, v11, v8, s80
	v_and_b32_sdwa v10, v1, v119 dst_sel:DWORD dst_unused:UNUSED_PAD src0_sel:WORD_1 src1_sel:DWORD
	v_and_b32_sdwa v11, v0, v119 dst_sel:DWORD dst_unused:UNUSED_PAD src0_sel:WORD_1 src1_sel:DWORD
	v_add3_u32 v1, v1, v10, s80
	v_add3_u32 v0, v0, v11, s80
	v_and_b32_e32 v1, 0xffff0000, v1
	v_and_b32_e32 v0, 0xffff0000, v0
	v_or_b32_sdwa v1, v1, v8 dst_sel:DWORD dst_unused:UNUSED_PAD src0_sel:DWORD src1_sel:WORD_1
	v_or_b32_sdwa v0, v0, v9 dst_sel:DWORD dst_unused:UNUSED_PAD src0_sel:DWORD src1_sel:WORD_1
	global_store_dwordx2 v[2:3], v[0:1], off
	v_mov_b32_e32 v8, v240
	v_mov_b32_e32 v9, v241
	v_mov_b32_e32 v10, v242
	v_mov_b32_e32 v11, v243
	v_add_u32_e32 v0, s4, v110
	ds_read_b128 v[0:3], v0
	s_waitcnt lgkmcnt(0)
	v_add_f32_e32 v1, v1, v9
	v_mul_f32_e32 v1, 0xbfb8aa3b, v1
	v_add_f32_e32 v0, v0, v8
	v_exp_f32_e32 v8, v1
	v_add_f32_e32 v1, v2, v10
	v_mul_f32_e32 v0, 0xbfb8aa3b, v0
	v_mul_f32_e32 v1, 0xbfb8aa3b, v1
	v_exp_f32_e32 v0, v0
	v_exp_f32_e32 v1, v1
	v_add_f32_e32 v2, v3, v11
	v_mul_f32_e32 v2, 0xbfb8aa3b, v2
	v_exp_f32_e32 v9, v2
	v_pk_add_f32 v[0:1], v[0:1], 1.0 op_sel_hi:[1,0]
	v_lshlrev_b64 v[2:3], 10, v[66:67]
	v_div_scale_f32 v10, s[6:7], v0, v0, 1.0
	v_rcp_f32_e32 v11, v10
	v_lshl_add_u64 v[2:3], v[6:7], 0, v[2:3]
	v_add_u32_e32 v66, 32, v66
	v_fma_f32 v12, -v10, v11, 1.0
	v_fmac_f32_e32 v11, v12, v11
	v_div_scale_f32 v12, vcc, 1.0, v0, 1.0
	v_mul_f32_e32 v13, v12, v11
	v_fma_f32 v14, -v10, v13, v12
	v_fmac_f32_e32 v13, v14, v11
	v_fma_f32 v10, -v10, v13, v12
	v_div_fmas_f32 v10, v10, v11, v13
	v_div_fixup_f32 v10, v10, v0, 1.0
	v_div_scale_f32 v0, s[6:7], v1, v1, 1.0
	v_rcp_f32_e32 v11, v0
	s_nop 0
	v_fma_f32 v12, -v0, v11, 1.0
	v_fmac_f32_e32 v11, v12, v11
	v_div_scale_f32 v12, vcc, 1.0, v1, 1.0
	v_mul_f32_e32 v13, v12, v11
	v_fma_f32 v14, -v0, v13, v12
	v_fmac_f32_e32 v13, v14, v11
	v_fma_f32 v0, -v0, v13, v12
	v_div_fmas_f32 v0, v0, v11, v13
	v_div_fixup_f32 v11, v0, v1, 1.0
	v_pk_add_f32 v[0:1], v[8:9], 1.0 op_sel_hi:[1,0]
	s_nop 0
	v_div_scale_f32 v8, s[6:7], v0, v0, 1.0
	v_rcp_f32_e32 v9, v8
	s_nop 0
	v_fma_f32 v12, -v8, v9, 1.0
	v_fmac_f32_e32 v9, v12, v9
	v_div_scale_f32 v12, vcc, 1.0, v0, 1.0
	v_mul_f32_e32 v13, v12, v9
	v_fma_f32 v14, -v8, v13, v12
	v_fmac_f32_e32 v13, v14, v9
	v_fma_f32 v8, -v8, v13, v12
	v_div_fmas_f32 v8, v8, v9, v13
	v_div_fixup_f32 v0, v8, v0, 1.0
	v_div_scale_f32 v8, s[6:7], v1, v1, 1.0
	v_rcp_f32_e32 v9, v8
	s_nop 0
	v_fma_f32 v12, -v8, v9, 1.0
	v_fmac_f32_e32 v9, v12, v9
	v_div_scale_f32 v12, vcc, 1.0, v1, 1.0
	v_mul_f32_e32 v13, v12, v9
	v_fma_f32 v14, -v8, v13, v12
	v_fmac_f32_e32 v13, v14, v9
	v_fma_f32 v8, -v8, v13, v12
	v_div_fmas_f32 v8, v8, v9, v13
	v_div_fixup_f32 v1, v8, v1, 1.0
	v_and_b32_sdwa v8, v11, v119 dst_sel:DWORD dst_unused:UNUSED_PAD src0_sel:WORD_1 src1_sel:DWORD
	v_and_b32_sdwa v9, v10, v119 dst_sel:DWORD dst_unused:UNUSED_PAD src0_sel:WORD_1 src1_sel:DWORD
	v_add3_u32 v9, v10, v9, s80
	v_add3_u32 v8, v11, v8, s80
	v_and_b32_sdwa v10, v1, v119 dst_sel:DWORD dst_unused:UNUSED_PAD src0_sel:WORD_1 src1_sel:DWORD
	v_and_b32_sdwa v11, v0, v119 dst_sel:DWORD dst_unused:UNUSED_PAD src0_sel:WORD_1 src1_sel:DWORD
	v_add3_u32 v1, v1, v10, s80
	v_add3_u32 v0, v0, v11, s80
	v_and_b32_e32 v1, 0xffff0000, v1
	v_and_b32_e32 v0, 0xffff0000, v0
	v_or_b32_sdwa v1, v1, v8 dst_sel:DWORD dst_unused:UNUSED_PAD src0_sel:DWORD src1_sel:WORD_1
	v_or_b32_sdwa v0, v0, v9 dst_sel:DWORD dst_unused:UNUSED_PAD src0_sel:DWORD src1_sel:WORD_1
	global_store_dwordx2 v[2:3], v[0:1], off
	v_mov_b32_e32 v8, v240
	v_mov_b32_e32 v9, v241
	v_mov_b32_e32 v10, v242
	v_mov_b32_e32 v11, v243
	v_add_u32_e32 v0, s4, v108
	ds_read_b128 v[0:3], v0
	s_addk_i32 s4, 0x4200
	s_cmp_lg_u32 s4, 0x10800
	s_waitcnt lgkmcnt(0)
	v_add_f32_e32 v1, v1, v9
	v_mul_f32_e32 v1, 0xbfb8aa3b, v1
	v_add_f32_e32 v0, v0, v8
	v_exp_f32_e32 v8, v1
	v_add_f32_e32 v1, v2, v10
	v_mul_f32_e32 v0, 0xbfb8aa3b, v0
	v_mul_f32_e32 v1, 0xbfb8aa3b, v1
	v_exp_f32_e32 v0, v0
	v_exp_f32_e32 v1, v1
	v_add_f32_e32 v2, v3, v11
	v_mul_f32_e32 v2, 0xbfb8aa3b, v2
	v_exp_f32_e32 v9, v2
	v_pk_add_f32 v[0:1], v[0:1], 1.0 op_sel_hi:[1,0]
	v_lshlrev_b64 v[2:3], 10, v[64:65]
	v_div_scale_f32 v10, s[6:7], v0, v0, 1.0
	v_rcp_f32_e32 v11, v10
	v_lshl_add_u64 v[2:3], v[6:7], 0, v[2:3]
	v_add_u32_e32 v64, 32, v64
	v_fma_f32 v12, -v10, v11, 1.0
	v_fmac_f32_e32 v11, v12, v11
	v_div_scale_f32 v12, vcc, 1.0, v0, 1.0
	v_mul_f32_e32 v13, v12, v11
	v_fma_f32 v14, -v10, v13, v12
	v_fmac_f32_e32 v13, v14, v11
	v_fma_f32 v10, -v10, v13, v12
	v_div_fmas_f32 v10, v10, v11, v13
	v_div_fixup_f32 v10, v10, v0, 1.0
	v_div_scale_f32 v0, s[6:7], v1, v1, 1.0
	v_rcp_f32_e32 v11, v0
	s_nop 0
	v_fma_f32 v12, -v0, v11, 1.0
	v_fmac_f32_e32 v11, v12, v11
	v_div_scale_f32 v12, vcc, 1.0, v1, 1.0
	v_mul_f32_e32 v13, v12, v11
	v_fma_f32 v14, -v0, v13, v12
	v_fmac_f32_e32 v13, v14, v11
	v_fma_f32 v0, -v0, v13, v12
	v_div_fmas_f32 v0, v0, v11, v13
	v_div_fixup_f32 v11, v0, v1, 1.0
	v_pk_add_f32 v[0:1], v[8:9], 1.0 op_sel_hi:[1,0]
	s_nop 0
	v_div_scale_f32 v8, s[6:7], v0, v0, 1.0
	v_rcp_f32_e32 v9, v8
	s_nop 0
	v_fma_f32 v12, -v8, v9, 1.0
	v_fmac_f32_e32 v9, v12, v9
	v_div_scale_f32 v12, vcc, 1.0, v0, 1.0
	v_mul_f32_e32 v13, v12, v9
	v_fma_f32 v14, -v8, v13, v12
	v_fmac_f32_e32 v13, v14, v9
	v_fma_f32 v8, -v8, v13, v12
	v_div_fmas_f32 v8, v8, v9, v13
	v_div_fixup_f32 v0, v8, v0, 1.0
	v_div_scale_f32 v8, s[6:7], v1, v1, 1.0
	v_rcp_f32_e32 v9, v8
	s_nop 0
	v_fma_f32 v12, -v8, v9, 1.0
	v_fmac_f32_e32 v9, v12, v9
	v_div_scale_f32 v12, vcc, 1.0, v1, 1.0
	v_mul_f32_e32 v13, v12, v9
	v_fma_f32 v14, -v8, v13, v12
	v_fmac_f32_e32 v13, v14, v9
	v_fma_f32 v8, -v8, v13, v12
	v_div_fmas_f32 v8, v8, v9, v13
	v_div_fixup_f32 v1, v8, v1, 1.0
	v_and_b32_sdwa v8, v11, v119 dst_sel:DWORD dst_unused:UNUSED_PAD src0_sel:WORD_1 src1_sel:DWORD
	v_and_b32_sdwa v9, v10, v119 dst_sel:DWORD dst_unused:UNUSED_PAD src0_sel:WORD_1 src1_sel:DWORD
	v_add3_u32 v9, v10, v9, s80
	v_add3_u32 v8, v11, v8, s80
	v_and_b32_sdwa v10, v1, v119 dst_sel:DWORD dst_unused:UNUSED_PAD src0_sel:WORD_1 src1_sel:DWORD
	v_and_b32_sdwa v11, v0, v119 dst_sel:DWORD dst_unused:UNUSED_PAD src0_sel:WORD_1 src1_sel:DWORD
	v_add3_u32 v1, v1, v10, s80
	v_add3_u32 v0, v0, v11, s80
	v_and_b32_e32 v1, 0xffff0000, v1
	v_and_b32_e32 v0, 0xffff0000, v0
	v_or_b32_sdwa v1, v1, v8 dst_sel:DWORD dst_unused:UNUSED_PAD src0_sel:DWORD src1_sel:WORD_1
	v_or_b32_sdwa v0, v0, v9 dst_sel:DWORD dst_unused:UNUSED_PAD src0_sel:DWORD src1_sel:WORD_1
	global_store_dwordx2 v[2:3], v[0:1], off
	s_cbranch_scc1 .LBB0_331
	s_add_i32 s0, s0, s33
	s_add_i32 s1, s1, s62
	s_cmpk_lt_i32 s0, 0x220
	s_barrier
	s_cbranch_scc1 .LBB0_306
